# write-through publish: each workgroup's last-tile epilogue stores before a grid barrier use sc1 (P1b, SchedA, SchedB, SchedC), other tiles unchanged
# speedup vs baseline: 1.0027x; 1.0027x over previous
; __device__ __forceinline__ unsigned pk_bf16(float lo, float hi) { const f32x2_t v = {lo, hi}; return __builtin_bit_cast(unsigned, __builtin_convertvector(v, bf16x2_t)); }
;     __device__ __forceinline__ bool operator()(f32x4 (&acc)[2][2][4][2], const Unit& u, int wr, int wc, int fr, int fq) const {
;     ...
;                     u32x4 w; w.x = pk_bf16(r0v[0], r0v[1]); w.y = pk_bf16(r0v[2], r0v[3]); w.z = pk_bf16(r1v[0], r1v[1]); w.w = pk_bf16(r1v[2], r1v[3]);
;                     *(u32x4*)(SGR + (size_t)row * D + ch0) = w;
;                     w.x = pk_bf16(s0v[0], s0v[1]); w.y = pk_bf16(s0v[2], s0v[3]); w.z = pk_bf16(s1v[0], s1v[1]); w.w = pk_bf16(s1v[2], s1v[3]);
;                     *(u32x4*)(SGB + (size_t)row * D + ch0) = w; }
.Lwt_p1b_1:
	global_store_dwordx4 v[138:139], v[134:137], off sc1
	s_branch .Lj_p1b_1

; __device__ __forceinline__ unsigned pk_bf16(float lo, float hi) { const f32x2_t v = {lo, hi}; return __builtin_bit_cast(unsigned, __builtin_convertvector(v, bf16x2_t)); }
;     __device__ __forceinline__ bool operator()(f32x4 (&acc)[2][2][4][2], const Unit& u, int wr, int wc, int fr, int fq) const {
;     ...
;                     u32x4 w; w.x = pk_bf16(r0v[0], r0v[1]); w.y = pk_bf16(r0v[2], r0v[3]); w.z = pk_bf16(r1v[0], r1v[1]); w.w = pk_bf16(r1v[2], r1v[3]);
;                     *(u32x4*)(SGR + (size_t)row * D + ch0) = w;
;                     w.x = pk_bf16(s0v[0], s0v[1]); w.y = pk_bf16(s0v[2], s0v[3]); w.z = pk_bf16(s1v[0], s1v[1]); w.w = pk_bf16(s1v[2], s1v[3]);
;                     *(u32x4*)(SGB + (size_t)row * D + ch0) = w; }
.Lwt_p1b_3:
	global_store_dwordx4 v[120:121], v[114:117], off sc1
	s_branch .Lj_p1b_3
.Lwt_p1b_4:
	global_store_dwordx4 v[118:119], v[114:117], off sc1
	s_branch .Lj_p1b_4
.Lwt_p1b_5:
	global_store_dwordx4 v[104:105], v[98:101], off sc1
	s_branch .Lj_p1b_5
.Lwt_p1b_6:
	global_store_dwordx4 v[102:103], v[98:101], off sc1
	s_branch .Lj_p1b_6
.Lwt_p1b_7:
	global_store_dwordx4 v[88:89], v[82:85], off sc1
	s_branch .Lj_p1b_7
.Lwt_p1b_8:
	global_store_dwordx4 v[86:87], v[82:85], off sc1
	s_branch .Lj_p1b_8
.Lwt_p1b_9:
	global_store_dwordx4 v[72:73], v[66:69], off sc1
	s_branch .Lj_p1b_9
.Lwt_p1b_10:
	global_store_dwordx4 v[70:71], v[66:69], off sc1
	s_branch .Lj_p1b_10
.Lwt_p1b_11:
	global_store_dwordx4 v[56:57], v[50:53], off sc1
	s_branch .Lj_p1b_11
.Lwt_p1b_12:
	global_store_dwordx4 v[54:55], v[50:53], off sc1
	s_branch .Lj_p1b_12
.Lwt_p1b_13:
	global_store_dwordx4 v[40:41], v[34:37], off sc1
	s_branch .Lj_p1b_13
.Lwt_p1b_14:
	global_store_dwordx4 v[8:9], v[2:5], off sc1
	s_branch .Lj_p1b_14
.Lwt_p1b_15:
	global_store_dwordx4 v[38:39], v[34:37], off sc1
	s_branch .Lj_p1b_15
.Lwt_p1b_16:
	global_store_dwordx4 v[6:7], v[2:5], off sc1
	s_branch .Lj_p1b_16

; __device__ __forceinline__ unsigned pk_bf16(float lo, float hi) { const f32x2_t v = {lo, hi}; return __builtin_bit_cast(unsigned, __builtin_convertvector(v, bf16x2_t)); }
;     __device__ __forceinline__ bool operator()(f32x4 (&acc)[2][2][4][2], const Unit& u, int wr, int wc, int fr, int fq) const {
;         const int pn = u.pn, r0 = u.pm * BM + wr * 64 + fr, cl = wc * 32 + fq * 8;
;         {
;             const int ch0 = (pn - 24) * 128 + cl;
;             const f32x4 ba0 = *(const f32x4*)(bgate + ch0), ba1 = *(const f32x4*)(bgate + ch0 + 4), bb0 = *(const f32x4*)(bgate + D + ch0), bb1 = *(const f32x4*)(bgate + D + ch0 + 4);
; #pragma unroll
;             for (int ai = 0; ai < 2; ++ai)
; #pragma unroll
;                 for (int m = 0; m < 4; ++m) { const int row = r0 + ai * HALF + m * 16;
;                     const f32x4 a0 = acc[ai][0][m][0] * gsc + ba0, a1 = acc[ai][0][m][1] * gsc + ba1, b0 = acc[ai][1][m][0] * gsc + bb0, b1 = acc[ai][1][m][1] * gsc + bb1;
;                     f32x4 r0v, r1v, s0v, s1v;
; #pragma unroll
;                     for (int j = 0; j < 4; ++j) {
;                         const float ea0 = __builtin_amdgcn_exp2f(-1.44269504f * fminf(fmaxf(a0[j], -40.f), 40.f)), eb0 = __builtin_amdgcn_exp2f(-1.44269504f * fminf(fmaxf(b0[j], -40.f), 40.f));
;                         const float ea1 = __builtin_amdgcn_exp2f(-1.44269504f * fminf(fmaxf(a1[j], -40.f), 40.f)), eb1 = __builtin_amdgcn_exp2f(-1.44269504f * fminf(fmaxf(b1[j], -40.f), 40.f));
;                         s0v[j] = __builtin_amdgcn_rcpf(1.0f + eb0); s1v[j] = __builtin_amdgcn_rcpf(1.0f + eb1);
;                         r0v[j] = (1.0f + eb0) * __builtin_amdgcn_rcpf(1.0f + ea0); r1v[j] = (1.0f + eb1) * __builtin_amdgcn_rcpf(1.0f + ea1); }
;                     u32x4 w; w.x = pk_bf16(r0v[0], r0v[1]); w.y = pk_bf16(r0v[2], r0v[3]); w.z = pk_bf16(r1v[0], r1v[1]); w.w = pk_bf16(r1v[2], r1v[3]);
;                     *(u32x4*)(SGR + (size_t)row * D + ch0) = w;
;                     w.x = pk_bf16(s0v[0], s0v[1]); w.y = pk_bf16(s0v[2], s0v[3]); w.z = pk_bf16(s1v[0], s1v[1]); w.w = pk_bf16(s1v[2], s1v[3]);
;                     *(u32x4*)(SGB + (size_t)row * D + ch0) = w; }
.Lkepi_p1b:
	v_lshl_add_u32 v160, s76, 7, v167
	v_ashrrev_i32_e32 v161, 31, v160
	v_lshlrev_b64 v[2:3], 2, v[160:161]
	s_nop 15
	s_nop 15
	v_lshl_add_u32 v158, s75, 8, v1
	s_and_b64 vcc, exec, s[42:43]
	s_mov_b32 s76, s73
	s_mov_b32 s75, s72
	s_mov_b64 s[46:47], s[2:3]
	s_mov_b64 s[50:51], s[44:45]
	s_nop 0
	v_fmamk_f32 v134, v134, 0x3c800000, v236
	v_fmamk_f32 v142, v142, 0x3c800000, v232
	v_fmamk_f32 v138, v138, 0x3c800000, v240
	v_fmamk_f32 v143, v143, 0x3c800000, v233
	v_fmamk_f32 v144, v144, 0x3c800000, v234
	v_fmamk_f32 v145, v145, 0x3c800000, v235
	v_fmamk_f32 v139, v139, 0x3c800000, v241
	v_fmamk_f32 v140, v140, 0x3c800000, v242
	v_med3_f32 v142, v142, s71, v172
	v_med3_f32 v138, v138, s71, v172
	v_med3_f32 v143, v143, s71, v172
	v_med3_f32 v144, v144, s71, v172
	v_med3_f32 v145, v145, s71, v172
	v_med3_f32 v139, v139, s71, v172
	v_med3_f32 v140, v140, s71, v172
	v_mul_f32_e32 v142, 0xbfb8aa3b, v142
	v_mul_f32_e32 v138, 0xbfb8aa3b, v138
	v_mul_f32_e32 v143, 0xbfb8aa3b, v143
	v_mul_f32_e32 v144, 0xbfb8aa3b, v144
	v_mul_f32_e32 v145, 0xbfb8aa3b, v145
	v_mul_f32_e32 v139, 0xbfb8aa3b, v139
	v_mul_f32_e32 v140, 0xbfb8aa3b, v140
	v_exp_f32_e32 v142, v142
	v_exp_f32_e32 v138, v138
	v_exp_f32_e32 v143, v143
	v_exp_f32_e32 v144, v144
	v_exp_f32_e32 v145, v145
	v_fmamk_f32 v130, v130, 0x3c800000, v244
	v_fmamk_f32 v135, v135, 0x3c800000, v237
	v_fmamk_f32 v136, v136, 0x3c800000, v238
	v_fmamk_f32 v137, v137, 0x3c800000, v239
	v_fmamk_f32 v141, v141, 0x3c800000, v243
	v_exp_f32_e32 v139, v139
	v_exp_f32_e32 v140, v140
	v_fmamk_f32 v131, v131, 0x3c800000, v245
	v_fmamk_f32 v132, v132, 0x3c800000, v246
	v_med3_f32 v134, v134, s71, v172
	v_med3_f32 v130, v130, s71, v172
	v_med3_f32 v135, v135, s71, v172
	v_med3_f32 v136, v136, s71, v172
	v_med3_f32 v137, v137, s71, v172
	v_med3_f32 v141, v141, s71, v172
	v_fmamk_f32 v133, v133, 0x3c800000, v247
	v_med3_f32 v131, v131, s71, v172
	v_med3_f32 v132, v132, s71, v172
	v_mul_f32_e32 v134, 0xbfb8aa3b, v134
	v_mul_f32_e32 v159, 0xbfb8aa3b, v130
	v_mul_f32_e32 v135, 0xbfb8aa3b, v135
	v_mul_f32_e32 v136, 0xbfb8aa3b, v136
	v_mul_f32_e32 v137, 0xbfb8aa3b, v137
	v_mul_f32_e32 v141, 0xbfb8aa3b, v141
	v_med3_f32 v133, v133, s71, v172
	v_mul_f32_e32 v162, 0xbfb8aa3b, v131
	v_mul_f32_e32 v163, 0xbfb8aa3b, v132
	v_exp_f32_e32 v130, v134
	v_exp_f32_e32 v132, v159
	v_exp_f32_e32 v131, v135
	v_exp_f32_e32 v134, v136
	v_exp_f32_e32 v135, v137
	v_exp_f32_e32 v159, v141
	v_add_f32_e32 v141, 1.0, v142
	v_add_f32_e32 v142, 1.0, v138
	v_add_f32_e32 v143, 1.0, v143
	v_add_f32_e32 v144, 1.0, v144
	v_add_f32_e32 v145, 1.0, v145
	v_mul_f32_e32 v164, 0xbfb8aa3b, v133
	v_exp_f32_e32 v133, v162
	v_exp_f32_e32 v136, v163
	v_add_f32_e32 v162, 1.0, v139
	v_add_f32_e32 v163, 1.0, v140
	v_rcp_f32_e32 v138, v141
	v_rcp_f32_e32 v140, v142
	v_rcp_f32_e32 v139, v143
	v_rcp_f32_e32 v142, v144
	v_rcp_f32_e32 v143, v145
	v_pk_add_f32 v[130:131], v[130:131], 1.0 op_sel_hi:[1,0]
	v_pk_add_f32 v[134:135], v[134:135], 1.0 op_sel_hi:[1,0]
	v_exp_f32_e32 v137, v164
	v_rcp_f32_e32 v164, v130
	v_rcp_f32_e32 v165, v131
	v_rcp_f32_e32 v141, v162
	v_rcp_f32_e32 v144, v163
	v_pk_mul_f32 v[130:131], v[138:139], v[130:131]
	v_rcp_f32_e32 v163, v134
	v_pk_mul_f32 v[138:139], v[142:143], v[134:135]
	v_add_f32_e32 v134, 1.0, v159
	v_rcp_f32_e32 v145, v134
	v_pk_add_f32 v[132:133], v[132:133], 1.0 op_sel_hi:[1,0]
	v_rcp_f32_e32 v142, v135
	v_rcp_f32_e32 v162, v132
	v_rcp_f32_e32 v173, v133
	v_pk_mul_f32 v[132:133], v[140:141], v[132:133]
	v_pk_add_f32 v[134:135], v[136:137], 1.0 op_sel_hi:[1,0]
	v_ashrrev_i32_e32 v159, 31, v158
	v_rcp_f32_e32 v143, v134
	v_pk_mul_f32 v[140:141], v[144:145], v[134:135]
	v_rcp_f32_e32 v144, v135
	v_cvt_pk_bf16_f32 v136, v132, v133
	v_lshlrev_b64 v[132:133], 12, v[158:159]
	v_cvt_pk_bf16_f32 v134, v130, v131
	v_cvt_pk_bf16_f32 v135, v138, v139
	v_lshl_add_u64 v[138:139], s[4:5], 0, v[132:133]
	v_lshlrev_b64 v[130:131], 1, v[160:161]
	v_cvt_pk_bf16_f32 v137, v140, v141
	v_lshl_add_u64 v[138:139], v[138:139], 0, v[130:131]
	v_fmamk_f32 v126, v126, 0x3c800000, v232
	v_fmamk_f32 v122, v122, 0x3c800000, v240
	v_fmamk_f32 v127, v127, 0x3c800000, v233
	s_cbranch_vccnz .Lwt_p1b_1
	global_store_dwordx4 v[138:139], v[134:137], off
.Lj_p1b_1:
	v_lshl_add_u64 v[138:139], s[14:15], 0, v[132:133]
	v_med3_f32 v126, v126, s71, v172
	v_med3_f32 v122, v122, s71, v172
	v_med3_f32 v127, v127, s71, v172
	v_cvt_pk_bf16_f32 v134, v164, v165
	v_cvt_pk_bf16_f32 v135, v163, v142
	v_cvt_pk_bf16_f32 v136, v162, v173
	v_cvt_pk_bf16_f32 v137, v143, v144
	v_lshl_add_u64 v[138:139], v[138:139], 0, v[130:131]
	v_mul_f32_e32 v126, 0xbfb8aa3b, v126
	v_mul_f32_e32 v122, 0xbfb8aa3b, v122
	v_mul_f32_e32 v127, 0xbfb8aa3b, v127
	s_cbranch_vccnz .Lwt_p1b_2
	global_store_dwordx4 v[138:139], v[134:137], off
; __device__ __forceinline__ unsigned pk_bf16(float lo, float hi) { const f32x2_t v = {lo, hi}; return __builtin_bit_cast(unsigned, __builtin_convertvector(v, bf16x2_t)); }
;     __device__ __forceinline__ bool operator()(f32x4 (&acc)[2][2][4][2], const Unit& u, int wr, int wc, int fr, int fq) const {
;     ...
;                 for (int m = 0; m < 4; ++m) { const int row = r0 + ai * HALF + m * 16;
;                     const f32x4 a0 = acc[ai][0][m][0] * gsc + ba0, a1 = acc[ai][0][m][1] * gsc + ba1, b0 = acc[ai][1][m][0] * gsc + bb0, b1 = acc[ai][1][m][1] * gsc + bb1;
;                     f32x4 r0v, r1v, s0v, s1v;
; #pragma unroll
;                     for (int j = 0; j < 4; ++j) {
;                         const float ea0 = __builtin_amdgcn_exp2f(-1.44269504f * fminf(fmaxf(a0[j], -40.f), 40.f)), eb0 = __builtin_amdgcn_exp2f(-1.44269504f * fminf(fmaxf(b0[j], -40.f), 40.f));
;                         const float ea1 = __builtin_amdgcn_exp2f(-1.44269504f * fminf(fmaxf(a1[j], -40.f), 40.f)), eb1 = __builtin_amdgcn_exp2f(-1.44269504f * fminf(fmaxf(b1[j], -40.f), 40.f));
;                         s0v[j] = __builtin_amdgcn_rcpf(1.0f + eb0); s1v[j] = __builtin_amdgcn_rcpf(1.0f + eb1);
;                         r0v[j] = (1.0f + eb0) * __builtin_amdgcn_rcpf(1.0f + ea0); r1v[j] = (1.0f + eb1) * __builtin_amdgcn_rcpf(1.0f + ea1); }
;                     u32x4 w; w.x = pk_bf16(r0v[0], r0v[1]); w.y = pk_bf16(r0v[2], r0v[3]); w.z = pk_bf16(r1v[0], r1v[1]); w.w = pk_bf16(r1v[2], r1v[3]);
;                     *(u32x4*)(SGR + (size_t)row * D + ch0) = w;
;                     w.x = pk_bf16(s0v[0], s0v[1]); w.y = pk_bf16(s0v[2], s0v[3]); w.z = pk_bf16(s1v[0], s1v[1]); w.w = pk_bf16(s1v[2], s1v[3]);
;                     *(u32x4*)(SGB + (size_t)row * D + ch0) = w; }
.Lj_p1b_2:
	v_exp_f32_e32 v126, v126
	v_exp_f32_e32 v127, v127
	v_exp_f32_e32 v134, v122
	v_fmamk_f32 v118, v118, 0x3c800000, v236
	v_fmamk_f32 v119, v119, 0x3c800000, v237
	v_fmamk_f32 v123, v123, 0x3c800000, v241
	v_med3_f32 v118, v118, s71, v172
	v_med3_f32 v119, v119, s71, v172
	v_med3_f32 v123, v123, s71, v172
	v_mul_f32_e32 v118, 0xbfb8aa3b, v118
	v_mul_f32_e32 v119, 0xbfb8aa3b, v119
	v_mul_f32_e32 v123, 0xbfb8aa3b, v123
	v_exp_f32_e32 v118, v118
	v_add_f32_e32 v122, 1.0, v126
	v_add_f32_e32 v126, 1.0, v134
	v_exp_f32_e32 v119, v119
	v_exp_f32_e32 v134, v123
	v_add_f32_e32 v123, 1.0, v127
	v_rcp_f32_e32 v122, v122
	v_rcp_f32_e32 v123, v123
	v_fmamk_f32 v114, v114, 0x3c800000, v244
	v_fmamk_f32 v115, v115, 0x3c800000, v245
	v_med3_f32 v114, v114, s71, v172
	v_med3_f32 v115, v115, s71, v172
	v_mul_f32_e32 v114, 0xbfb8aa3b, v114
	v_mul_f32_e32 v115, 0xbfb8aa3b, v115
	v_pk_add_f32 v[118:119], v[118:119], 1.0 op_sel_hi:[1,0]
	v_exp_f32_e32 v114, v114
	v_exp_f32_e32 v115, v115
	v_rcp_f32_e32 v135, v118
	v_pk_mul_f32 v[122:123], v[122:123], v[118:119]
	v_add_f32_e32 v118, 1.0, v134
	v_rcp_f32_e32 v126, v126
	v_rcp_f32_e32 v127, v118
	v_pk_add_f32 v[114:115], v[114:115], 1.0 op_sel_hi:[1,0]
	v_rcp_f32_e32 v134, v119
	v_rcp_f32_e32 v136, v114
	v_pk_mul_f32 v[118:119], v[126:127], v[114:115]
	v_fmamk_f32 v114, v128, 0x3c800000, v234
	v_med3_f32 v114, v114, s71, v172
	v_mul_f32_e32 v114, 0xbfb8aa3b, v114
	v_rcp_f32_e32 v137, v115
	v_exp_f32_e32 v115, v114
	v_fmamk_f32 v114, v120, 0x3c800000, v238
	v_fmamk_f32 v120, v124, 0x3c800000, v242
	v_med3_f32 v120, v120, s71, v172
	v_mul_f32_e32 v120, 0xbfb8aa3b, v120
	v_exp_f32_e32 v124, v120
	v_add_f32_e32 v115, 1.0, v115
	v_rcp_f32_e32 v120, v115
	v_med3_f32 v114, v114, s71, v172
	v_add_f32_e32 v115, 1.0, v124
	v_rcp_f32_e32 v124, v115
	v_fmamk_f32 v115, v129, 0x3c800000, v235
	v_med3_f32 v115, v115, s71, v172
	v_mul_f32_e32 v115, 0xbfb8aa3b, v115
	v_exp_f32_e32 v126, v115
	v_fmamk_f32 v115, v121, 0x3c800000, v239
	v_fmamk_f32 v121, v125, 0x3c800000, v243
	v_med3_f32 v115, v115, s71, v172
	v_med3_f32 v121, v121, s71, v172
	v_mul_f32_e32 v114, 0xbfb8aa3b, v114
	v_mul_f32_e32 v115, 0xbfb8aa3b, v115
	v_mul_f32_e32 v121, 0xbfb8aa3b, v121
	v_exp_f32_e32 v114, v114
	v_fmamk_f32 v116, v116, 0x3c800000, v246
	v_exp_f32_e32 v115, v115
	v_exp_f32_e32 v125, v121
	v_fmamk_f32 v117, v117, 0x3c800000, v247
	v_add_f32_e32 v121, 1.0, v126
	v_med3_f32 v116, v116, s71, v172
	v_med3_f32 v117, v117, s71, v172
	v_rcp_f32_e32 v121, v121
	v_mul_f32_e32 v116, 0xbfb8aa3b, v116
	v_mul_f32_e32 v117, 0xbfb8aa3b, v117
	v_exp_f32_e32 v116, v116
	v_exp_f32_e32 v117, v117
	v_pk_add_f32 v[114:115], v[114:115], 1.0 op_sel_hi:[1,0]
	v_or_b32_e32 v126, 16, v158
	v_rcp_f32_e32 v128, v114
	v_pk_mul_f32 v[120:121], v[120:121], v[114:115]
	v_add_f32_e32 v114, 1.0, v125
	v_rcp_f32_e32 v125, v114
	v_rcp_f32_e32 v129, v115
	v_pk_add_f32 v[114:115], v[116:117], 1.0 op_sel_hi:[1,0]
	v_ashrrev_i32_e32 v127, 31, v126
	v_rcp_f32_e32 v138, v114
	v_rcp_f32_e32 v139, v115
	v_cvt_pk_bf16_f32 v116, v118, v119
	v_lshlrev_b64 v[118:119], 12, v[126:127]
	v_pk_mul_f32 v[124:125], v[124:125], v[114:115]
	v_cvt_pk_bf16_f32 v115, v120, v121
	v_lshl_add_u64 v[120:121], s[4:5], 0, v[118:119]
	v_fmamk_f32 v110, v110, 0x3c800000, v232
	v_fmamk_f32 v106, v106, 0x3c800000, v240
	v_fmamk_f32 v111, v111, 0x3c800000, v233
	v_cvt_pk_bf16_f32 v114, v122, v123
	v_cvt_pk_bf16_f32 v117, v124, v125
	v_lshl_add_u64 v[120:121], v[120:121], 0, v[130:131]
	v_lshl_add_u64 v[118:119], s[14:15], 0, v[118:119]
	v_med3_f32 v110, v110, s71, v172
	v_med3_f32 v106, v106, s71, v172
	v_med3_f32 v111, v111, s71, v172
	s_cbranch_vccnz .Lwt_p1b_3
	global_store_dwordx4 v[120:121], v[114:117], off
.Lj_p1b_3:
	v_lshl_add_u64 v[118:119], v[118:119], 0, v[130:131]
	v_mul_f32_e32 v110, 0xbfb8aa3b, v110
	v_cvt_pk_bf16_f32 v114, v135, v134
	v_cvt_pk_bf16_f32 v115, v128, v129
	v_cvt_pk_bf16_f32 v116, v136, v137
	v_cvt_pk_bf16_f32 v117, v138, v139
	v_mul_f32_e32 v106, 0xbfb8aa3b, v106
	v_mul_f32_e32 v111, 0xbfb8aa3b, v111
	s_cbranch_vccnz .Lwt_p1b_4
	global_store_dwordx4 v[118:119], v[114:117], off
.Lj_p1b_4:
	v_exp_f32_e32 v110, v110
	v_exp_f32_e32 v111, v111
	v_exp_f32_e32 v114, v106
	v_fmamk_f32 v102, v102, 0x3c800000, v236
	v_fmamk_f32 v103, v103, 0x3c800000, v237
	v_fmamk_f32 v107, v107, 0x3c800000, v241
	v_med3_f32 v102, v102, s71, v172
	v_med3_f32 v103, v103, s71, v172
	v_med3_f32 v107, v107, s71, v172
	v_mul_f32_e32 v102, 0xbfb8aa3b, v102
	v_mul_f32_e32 v103, 0xbfb8aa3b, v103
	v_mul_f32_e32 v107, 0xbfb8aa3b, v107
	v_exp_f32_e32 v102, v102
	v_add_f32_e32 v106, 1.0, v110
	v_add_f32_e32 v110, 1.0, v114
	v_exp_f32_e32 v103, v103
	v_exp_f32_e32 v114, v107
	v_add_f32_e32 v107, 1.0, v111
	v_rcp_f32_e32 v106, v106
	v_rcp_f32_e32 v107, v107
	v_fmamk_f32 v98, v98, 0x3c800000, v244
	v_fmamk_f32 v99, v99, 0x3c800000, v245
	v_med3_f32 v98, v98, s71, v172
	v_med3_f32 v99, v99, s71, v172
	v_mul_f32_e32 v98, 0xbfb8aa3b, v98
	v_mul_f32_e32 v99, 0xbfb8aa3b, v99
	v_pk_add_f32 v[102:103], v[102:103], 1.0 op_sel_hi:[1,0]
	v_exp_f32_e32 v98, v98
	v_exp_f32_e32 v99, v99
	v_rcp_f32_e32 v115, v102
	v_pk_mul_f32 v[106:107], v[106:107], v[102:103]
	v_add_f32_e32 v102, 1.0, v114
	v_rcp_f32_e32 v110, v110
	v_rcp_f32_e32 v111, v102
	v_pk_add_f32 v[98:99], v[98:99], 1.0 op_sel_hi:[1,0]
	v_rcp_f32_e32 v114, v103
	v_rcp_f32_e32 v116, v98
	v_pk_mul_f32 v[102:103], v[110:111], v[98:99]
	v_fmamk_f32 v98, v112, 0x3c800000, v234
	v_med3_f32 v98, v98, s71, v172
	v_mul_f32_e32 v98, 0xbfb8aa3b, v98
	v_rcp_f32_e32 v117, v99
	v_exp_f32_e32 v99, v98
	v_fmamk_f32 v98, v104, 0x3c800000, v238
	v_fmamk_f32 v104, v108, 0x3c800000, v242
; __device__ __forceinline__ unsigned pk_bf16(float lo, float hi) { const f32x2_t v = {lo, hi}; return __builtin_bit_cast(unsigned, __builtin_convertvector(v, bf16x2_t)); }
;     __device__ __forceinline__ bool operator()(f32x4 (&acc)[2][2][4][2], const Unit& u, int wr, int wc, int fr, int fq) const {
;     ...
;                 for (int m = 0; m < 4; ++m) { const int row = r0 + ai * HALF + m * 16;
;                     const f32x4 a0 = acc[ai][0][m][0] * gsc + ba0, a1 = acc[ai][0][m][1] * gsc + ba1, b0 = acc[ai][1][m][0] * gsc + bb0, b1 = acc[ai][1][m][1] * gsc + bb1;
;                     f32x4 r0v, r1v, s0v, s1v;
; #pragma unroll
;                     for (int j = 0; j < 4; ++j) {
;                         const float ea0 = __builtin_amdgcn_exp2f(-1.44269504f * fminf(fmaxf(a0[j], -40.f), 40.f)), eb0 = __builtin_amdgcn_exp2f(-1.44269504f * fminf(fmaxf(b0[j], -40.f), 40.f));
;                         const float ea1 = __builtin_amdgcn_exp2f(-1.44269504f * fminf(fmaxf(a1[j], -40.f), 40.f)), eb1 = __builtin_amdgcn_exp2f(-1.44269504f * fminf(fmaxf(b1[j], -40.f), 40.f));
;                         s0v[j] = __builtin_amdgcn_rcpf(1.0f + eb0); s1v[j] = __builtin_amdgcn_rcpf(1.0f + eb1);
;                         r0v[j] = (1.0f + eb0) * __builtin_amdgcn_rcpf(1.0f + ea0); r1v[j] = (1.0f + eb1) * __builtin_amdgcn_rcpf(1.0f + ea1); }
;                     u32x4 w; w.x = pk_bf16(r0v[0], r0v[1]); w.y = pk_bf16(r0v[2], r0v[3]); w.z = pk_bf16(r1v[0], r1v[1]); w.w = pk_bf16(r1v[2], r1v[3]);
;                     *(u32x4*)(SGR + (size_t)row * D + ch0) = w;
;                     w.x = pk_bf16(s0v[0], s0v[1]); w.y = pk_bf16(s0v[2], s0v[3]); w.z = pk_bf16(s1v[0], s1v[1]); w.w = pk_bf16(s1v[2], s1v[3]);
;                     *(u32x4*)(SGB + (size_t)row * D + ch0) = w; }
	v_med3_f32 v104, v104, s71, v172
	v_mul_f32_e32 v104, 0xbfb8aa3b, v104
	v_exp_f32_e32 v108, v104
	v_add_f32_e32 v99, 1.0, v99
	v_rcp_f32_e32 v104, v99
	v_med3_f32 v98, v98, s71, v172
	v_add_f32_e32 v99, 1.0, v108
	v_rcp_f32_e32 v108, v99
	v_fmamk_f32 v99, v113, 0x3c800000, v235
	v_med3_f32 v99, v99, s71, v172
	v_mul_f32_e32 v99, 0xbfb8aa3b, v99
	v_exp_f32_e32 v110, v99
	v_fmamk_f32 v99, v105, 0x3c800000, v239
	v_fmamk_f32 v105, v109, 0x3c800000, v243
	v_med3_f32 v99, v99, s71, v172
	v_med3_f32 v105, v105, s71, v172
	v_mul_f32_e32 v98, 0xbfb8aa3b, v98
	v_mul_f32_e32 v99, 0xbfb8aa3b, v99
	v_mul_f32_e32 v105, 0xbfb8aa3b, v105
	v_exp_f32_e32 v98, v98
	v_fmamk_f32 v100, v100, 0x3c800000, v246
	v_exp_f32_e32 v99, v99
	v_exp_f32_e32 v109, v105
	v_fmamk_f32 v101, v101, 0x3c800000, v247
	v_add_f32_e32 v105, 1.0, v110
	v_med3_f32 v100, v100, s71, v172
	v_med3_f32 v101, v101, s71, v172
	v_rcp_f32_e32 v105, v105
	v_mul_f32_e32 v100, 0xbfb8aa3b, v100
	v_mul_f32_e32 v101, 0xbfb8aa3b, v101
	v_exp_f32_e32 v100, v100
	v_exp_f32_e32 v101, v101
	v_pk_add_f32 v[98:99], v[98:99], 1.0 op_sel_hi:[1,0]
	v_or_b32_e32 v110, 32, v158
	v_rcp_f32_e32 v112, v98
	v_pk_mul_f32 v[104:105], v[104:105], v[98:99]
	v_add_f32_e32 v98, 1.0, v109
	v_rcp_f32_e32 v109, v98
	v_rcp_f32_e32 v113, v99
	v_pk_add_f32 v[98:99], v[100:101], 1.0 op_sel_hi:[1,0]
	v_ashrrev_i32_e32 v111, 31, v110
	v_rcp_f32_e32 v118, v98
	v_rcp_f32_e32 v119, v99
	v_cvt_pk_bf16_f32 v100, v102, v103
	v_lshlrev_b64 v[102:103], 12, v[110:111]
	v_pk_mul_f32 v[108:109], v[108:109], v[98:99]
	v_cvt_pk_bf16_f32 v99, v104, v105
	v_lshl_add_u64 v[104:105], s[4:5], 0, v[102:103]
	v_fmamk_f32 v94, v94, 0x3c800000, v232
	v_fmamk_f32 v90, v90, 0x3c800000, v240
	v_fmamk_f32 v95, v95, 0x3c800000, v233
	v_cvt_pk_bf16_f32 v98, v106, v107
	v_cvt_pk_bf16_f32 v101, v108, v109
	v_lshl_add_u64 v[104:105], v[104:105], 0, v[130:131]
	v_lshl_add_u64 v[102:103], s[14:15], 0, v[102:103]
	v_med3_f32 v94, v94, s71, v172
	v_med3_f32 v90, v90, s71, v172
	v_med3_f32 v95, v95, s71, v172
	s_cbranch_vccnz .Lwt_p1b_5
	global_store_dwordx4 v[104:105], v[98:101], off
.Lj_p1b_5:
	v_lshl_add_u64 v[102:103], v[102:103], 0, v[130:131]
	v_mul_f32_e32 v94, 0xbfb8aa3b, v94
	v_cvt_pk_bf16_f32 v98, v115, v114
	v_cvt_pk_bf16_f32 v99, v112, v113
	v_cvt_pk_bf16_f32 v100, v116, v117
	v_cvt_pk_bf16_f32 v101, v118, v119
	v_mul_f32_e32 v90, 0xbfb8aa3b, v90
	v_mul_f32_e32 v95, 0xbfb8aa3b, v95
	s_cbranch_vccnz .Lwt_p1b_6
	global_store_dwordx4 v[102:103], v[98:101], off
.Lj_p1b_6:
	v_exp_f32_e32 v94, v94
	v_exp_f32_e32 v95, v95
	v_exp_f32_e32 v98, v90
	v_fmamk_f32 v86, v86, 0x3c800000, v236
	v_fmamk_f32 v87, v87, 0x3c800000, v237
	v_fmamk_f32 v91, v91, 0x3c800000, v241
	v_med3_f32 v86, v86, s71, v172
	v_med3_f32 v87, v87, s71, v172
	v_med3_f32 v91, v91, s71, v172
	v_mul_f32_e32 v86, 0xbfb8aa3b, v86
	v_mul_f32_e32 v87, 0xbfb8aa3b, v87
	v_mul_f32_e32 v91, 0xbfb8aa3b, v91
	v_exp_f32_e32 v86, v86
	v_add_f32_e32 v90, 1.0, v94
	v_add_f32_e32 v94, 1.0, v98
	v_exp_f32_e32 v87, v87
	v_exp_f32_e32 v98, v91
	v_add_f32_e32 v91, 1.0, v95
	v_rcp_f32_e32 v90, v90
	v_rcp_f32_e32 v91, v91
	v_fmamk_f32 v82, v82, 0x3c800000, v244
	v_fmamk_f32 v83, v83, 0x3c800000, v245
	v_med3_f32 v82, v82, s71, v172
	v_med3_f32 v83, v83, s71, v172
	v_mul_f32_e32 v82, 0xbfb8aa3b, v82
	v_mul_f32_e32 v83, 0xbfb8aa3b, v83
	v_pk_add_f32 v[86:87], v[86:87], 1.0 op_sel_hi:[1,0]
	v_exp_f32_e32 v82, v82
	v_exp_f32_e32 v83, v83
	v_rcp_f32_e32 v99, v86
	v_pk_mul_f32 v[90:91], v[90:91], v[86:87]
	v_add_f32_e32 v86, 1.0, v98
	v_rcp_f32_e32 v94, v94
	v_rcp_f32_e32 v95, v86
	v_pk_add_f32 v[82:83], v[82:83], 1.0 op_sel_hi:[1,0]
	v_rcp_f32_e32 v98, v87
	v_rcp_f32_e32 v100, v82
	v_pk_mul_f32 v[86:87], v[94:95], v[82:83]
	v_fmamk_f32 v82, v96, 0x3c800000, v234
	v_med3_f32 v82, v82, s71, v172
	v_mul_f32_e32 v82, 0xbfb8aa3b, v82
	v_rcp_f32_e32 v101, v83
	v_exp_f32_e32 v83, v82
	v_fmamk_f32 v82, v88, 0x3c800000, v238
	v_fmamk_f32 v88, v92, 0x3c800000, v242
	v_med3_f32 v88, v88, s71, v172
	v_mul_f32_e32 v88, 0xbfb8aa3b, v88
	v_exp_f32_e32 v92, v88
	v_add_f32_e32 v83, 1.0, v83
	v_rcp_f32_e32 v88, v83
	v_med3_f32 v82, v82, s71, v172
	v_add_f32_e32 v83, 1.0, v92
	v_rcp_f32_e32 v92, v83
	v_fmamk_f32 v83, v97, 0x3c800000, v235
	v_med3_f32 v83, v83, s71, v172
	v_mul_f32_e32 v83, 0xbfb8aa3b, v83
	v_exp_f32_e32 v94, v83
	v_fmamk_f32 v83, v89, 0x3c800000, v239
	v_fmamk_f32 v89, v93, 0x3c800000, v243
	v_med3_f32 v83, v83, s71, v172
	v_med3_f32 v89, v89, s71, v172
	v_mul_f32_e32 v82, 0xbfb8aa3b, v82
	v_mul_f32_e32 v83, 0xbfb8aa3b, v83
	v_mul_f32_e32 v89, 0xbfb8aa3b, v89
	v_exp_f32_e32 v82, v82
	v_fmamk_f32 v84, v84, 0x3c800000, v246
	v_exp_f32_e32 v83, v83
	v_exp_f32_e32 v93, v89
	v_fmamk_f32 v85, v85, 0x3c800000, v247
	v_add_f32_e32 v89, 1.0, v94
	v_med3_f32 v84, v84, s71, v172
	v_med3_f32 v85, v85, s71, v172
	v_rcp_f32_e32 v89, v89
	v_mul_f32_e32 v84, 0xbfb8aa3b, v84
	v_mul_f32_e32 v85, 0xbfb8aa3b, v85
	v_exp_f32_e32 v84, v84
	v_exp_f32_e32 v85, v85
	v_pk_add_f32 v[82:83], v[82:83], 1.0 op_sel_hi:[1,0]
	v_or_b32_e32 v94, 48, v158
	v_rcp_f32_e32 v96, v82
	v_pk_mul_f32 v[88:89], v[88:89], v[82:83]
	v_add_f32_e32 v82, 1.0, v93
	v_rcp_f32_e32 v93, v82
	v_rcp_f32_e32 v97, v83
	v_pk_add_f32 v[82:83], v[84:85], 1.0 op_sel_hi:[1,0]
	v_ashrrev_i32_e32 v95, 31, v94
	v_rcp_f32_e32 v102, v82
	v_rcp_f32_e32 v103, v83
	v_cvt_pk_bf16_f32 v84, v86, v87
	v_lshlrev_b64 v[86:87], 12, v[94:95]
	v_pk_mul_f32 v[92:93], v[92:93], v[82:83]
	v_cvt_pk_bf16_f32 v83, v88, v89
	v_lshl_add_u64 v[88:89], s[4:5], 0, v[86:87]
	v_fmamk_f32 v78, v78, 0x3c800000, v232
	v_fmamk_f32 v74, v74, 0x3c800000, v240
	v_fmamk_f32 v79, v79, 0x3c800000, v233
	v_cvt_pk_bf16_f32 v82, v90, v91
	v_cvt_pk_bf16_f32 v85, v92, v93
	v_lshl_add_u64 v[88:89], v[88:89], 0, v[130:131]
	v_lshl_add_u64 v[86:87], s[14:15], 0, v[86:87]
	v_med3_f32 v78, v78, s71, v172
	v_med3_f32 v74, v74, s71, v172
	v_med3_f32 v79, v79, s71, v172
	s_cbranch_vccnz .Lwt_p1b_7
	global_store_dwordx4 v[88:89], v[82:85], off
; __device__ __forceinline__ unsigned pk_bf16(float lo, float hi) { const f32x2_t v = {lo, hi}; return __builtin_bit_cast(unsigned, __builtin_convertvector(v, bf16x2_t)); }
;     __device__ __forceinline__ bool operator()(f32x4 (&acc)[2][2][4][2], const Unit& u, int wr, int wc, int fr, int fq) const {
;     ...
;                 for (int m = 0; m < 4; ++m) { const int row = r0 + ai * HALF + m * 16;
;                     const f32x4 a0 = acc[ai][0][m][0] * gsc + ba0, a1 = acc[ai][0][m][1] * gsc + ba1, b0 = acc[ai][1][m][0] * gsc + bb0, b1 = acc[ai][1][m][1] * gsc + bb1;
;                     f32x4 r0v, r1v, s0v, s1v;
; #pragma unroll
;                     for (int j = 0; j < 4; ++j) {
;                         const float ea0 = __builtin_amdgcn_exp2f(-1.44269504f * fminf(fmaxf(a0[j], -40.f), 40.f)), eb0 = __builtin_amdgcn_exp2f(-1.44269504f * fminf(fmaxf(b0[j], -40.f), 40.f));
;                         const float ea1 = __builtin_amdgcn_exp2f(-1.44269504f * fminf(fmaxf(a1[j], -40.f), 40.f)), eb1 = __builtin_amdgcn_exp2f(-1.44269504f * fminf(fmaxf(b1[j], -40.f), 40.f));
;                         s0v[j] = __builtin_amdgcn_rcpf(1.0f + eb0); s1v[j] = __builtin_amdgcn_rcpf(1.0f + eb1);
;                         r0v[j] = (1.0f + eb0) * __builtin_amdgcn_rcpf(1.0f + ea0); r1v[j] = (1.0f + eb1) * __builtin_amdgcn_rcpf(1.0f + ea1); }
;                     u32x4 w; w.x = pk_bf16(r0v[0], r0v[1]); w.y = pk_bf16(r0v[2], r0v[3]); w.z = pk_bf16(r1v[0], r1v[1]); w.w = pk_bf16(r1v[2], r1v[3]);
;                     *(u32x4*)(SGR + (size_t)row * D + ch0) = w;
;                     w.x = pk_bf16(s0v[0], s0v[1]); w.y = pk_bf16(s0v[2], s0v[3]); w.z = pk_bf16(s1v[0], s1v[1]); w.w = pk_bf16(s1v[2], s1v[3]);
;                     *(u32x4*)(SGB + (size_t)row * D + ch0) = w; }
.Lj_p1b_7:
	v_lshl_add_u64 v[86:87], v[86:87], 0, v[130:131]
	v_mul_f32_e32 v78, 0xbfb8aa3b, v78
	v_cvt_pk_bf16_f32 v82, v99, v98
	v_cvt_pk_bf16_f32 v83, v96, v97
	v_cvt_pk_bf16_f32 v84, v100, v101
	v_cvt_pk_bf16_f32 v85, v102, v103
	v_mul_f32_e32 v74, 0xbfb8aa3b, v74
	v_mul_f32_e32 v79, 0xbfb8aa3b, v79
	s_cbranch_vccnz .Lwt_p1b_8
	global_store_dwordx4 v[86:87], v[82:85], off
.Lj_p1b_8:
	v_exp_f32_e32 v78, v78
	v_exp_f32_e32 v79, v79
	v_exp_f32_e32 v82, v74
	v_fmamk_f32 v70, v70, 0x3c800000, v236
	v_fmamk_f32 v71, v71, 0x3c800000, v237
	v_fmamk_f32 v75, v75, 0x3c800000, v241
	v_med3_f32 v70, v70, s71, v172
	v_med3_f32 v71, v71, s71, v172
	v_med3_f32 v75, v75, s71, v172
	v_mul_f32_e32 v70, 0xbfb8aa3b, v70
	v_mul_f32_e32 v71, 0xbfb8aa3b, v71
	v_mul_f32_e32 v75, 0xbfb8aa3b, v75
	v_exp_f32_e32 v70, v70
	v_add_f32_e32 v74, 1.0, v78
	v_add_f32_e32 v78, 1.0, v82
	v_exp_f32_e32 v71, v71
	v_exp_f32_e32 v82, v75
	v_add_f32_e32 v75, 1.0, v79
	v_rcp_f32_e32 v74, v74
	v_rcp_f32_e32 v75, v75
	v_fmamk_f32 v66, v66, 0x3c800000, v244
	v_fmamk_f32 v67, v67, 0x3c800000, v245
	v_med3_f32 v66, v66, s71, v172
	v_med3_f32 v67, v67, s71, v172
	v_mul_f32_e32 v66, 0xbfb8aa3b, v66
	v_mul_f32_e32 v67, 0xbfb8aa3b, v67
	v_pk_add_f32 v[70:71], v[70:71], 1.0 op_sel_hi:[1,0]
	v_exp_f32_e32 v66, v66
	v_exp_f32_e32 v67, v67
	v_rcp_f32_e32 v83, v70
	v_pk_mul_f32 v[74:75], v[74:75], v[70:71]
	v_add_f32_e32 v70, 1.0, v82
	v_rcp_f32_e32 v78, v78
	v_rcp_f32_e32 v79, v70
	v_pk_add_f32 v[66:67], v[66:67], 1.0 op_sel_hi:[1,0]
	v_rcp_f32_e32 v82, v71
	v_rcp_f32_e32 v84, v66
	v_pk_mul_f32 v[70:71], v[78:79], v[66:67]
	v_fmamk_f32 v66, v80, 0x3c800000, v234
	v_med3_f32 v66, v66, s71, v172
	v_mul_f32_e32 v66, 0xbfb8aa3b, v66
	v_rcp_f32_e32 v78, v67
	v_exp_f32_e32 v67, v66
	v_fmamk_f32 v66, v72, 0x3c800000, v238
	v_fmamk_f32 v72, v76, 0x3c800000, v242
	v_med3_f32 v72, v72, s71, v172
	v_mul_f32_e32 v72, 0xbfb8aa3b, v72
	v_exp_f32_e32 v76, v72
	v_add_f32_e32 v67, 1.0, v67
	v_rcp_f32_e32 v72, v67
	v_med3_f32 v66, v66, s71, v172
	v_add_f32_e32 v67, 1.0, v76
	v_rcp_f32_e32 v76, v67
	v_fmamk_f32 v67, v81, 0x3c800000, v235
	v_med3_f32 v67, v67, s71, v172
	v_mul_f32_e32 v67, 0xbfb8aa3b, v67
	v_exp_f32_e32 v79, v67
	v_fmamk_f32 v67, v73, 0x3c800000, v239
	v_fmamk_f32 v73, v77, 0x3c800000, v243
	v_med3_f32 v67, v67, s71, v172
	v_med3_f32 v73, v73, s71, v172
	v_mul_f32_e32 v66, 0xbfb8aa3b, v66
	v_mul_f32_e32 v67, 0xbfb8aa3b, v67
	v_mul_f32_e32 v73, 0xbfb8aa3b, v73
	v_exp_f32_e32 v66, v66
	v_fmamk_f32 v68, v68, 0x3c800000, v246
	v_exp_f32_e32 v67, v67
	v_exp_f32_e32 v77, v73
	v_fmamk_f32 v69, v69, 0x3c800000, v247
	v_add_f32_e32 v73, 1.0, v79
	v_med3_f32 v68, v68, s71, v172
	v_med3_f32 v69, v69, s71, v172
	v_rcp_f32_e32 v73, v73
	v_mul_f32_e32 v68, 0xbfb8aa3b, v68
	v_mul_f32_e32 v69, 0xbfb8aa3b, v69
	v_exp_f32_e32 v68, v68
	v_exp_f32_e32 v69, v69
	v_pk_add_f32 v[66:67], v[66:67], 1.0 op_sel_hi:[1,0]
	v_fmamk_f32 v62, v62, 0x3c800000, v232
	v_rcp_f32_e32 v79, v66
	v_pk_mul_f32 v[72:73], v[72:73], v[66:67]
	v_add_f32_e32 v66, 1.0, v77
	v_rcp_f32_e32 v77, v66
	v_rcp_f32_e32 v80, v67
	v_pk_add_f32 v[66:67], v[68:69], 1.0 op_sel_hi:[1,0]
	v_cvt_pk_bf16_f32 v68, v70, v71
	v_rcp_f32_e32 v81, v66
	v_rcp_f32_e32 v85, v67
	v_lshl_add_u64 v[70:71], v[132:133], 0, s[18:19]
	v_pk_mul_f32 v[76:77], v[76:77], v[66:67]
	v_cvt_pk_bf16_f32 v67, v72, v73
	v_lshl_add_u64 v[72:73], s[4:5], 0, v[70:71]
	v_fmamk_f32 v58, v58, 0x3c800000, v240
	v_fmamk_f32 v63, v63, 0x3c800000, v233
	v_cvt_pk_bf16_f32 v66, v74, v75
	v_cvt_pk_bf16_f32 v69, v76, v77
	v_lshl_add_u64 v[72:73], v[72:73], 0, v[130:131]
	v_lshl_add_u64 v[70:71], s[14:15], 0, v[70:71]
	v_med3_f32 v62, v62, s71, v172
	v_med3_f32 v58, v58, s71, v172
	v_med3_f32 v63, v63, s71, v172
	s_cbranch_vccnz .Lwt_p1b_9
	global_store_dwordx4 v[72:73], v[66:69], off
.Lj_p1b_9:
	v_lshl_add_u64 v[70:71], v[70:71], 0, v[130:131]
	v_mul_f32_e32 v62, 0xbfb8aa3b, v62
	v_cvt_pk_bf16_f32 v66, v83, v82
	v_cvt_pk_bf16_f32 v67, v79, v80
	v_cvt_pk_bf16_f32 v68, v84, v78
	v_cvt_pk_bf16_f32 v69, v81, v85
	v_mul_f32_e32 v58, 0xbfb8aa3b, v58
	v_mul_f32_e32 v63, 0xbfb8aa3b, v63
	s_cbranch_vccnz .Lwt_p1b_10
	global_store_dwordx4 v[70:71], v[66:69], off
.Lj_p1b_10:
	v_exp_f32_e32 v62, v62
	v_exp_f32_e32 v63, v63
	v_exp_f32_e32 v66, v58
	v_fmamk_f32 v54, v54, 0x3c800000, v236
	v_fmamk_f32 v55, v55, 0x3c800000, v237
	v_fmamk_f32 v59, v59, 0x3c800000, v241
	v_med3_f32 v54, v54, s71, v172
	v_med3_f32 v55, v55, s71, v172
	v_med3_f32 v59, v59, s71, v172
	v_mul_f32_e32 v54, 0xbfb8aa3b, v54
	v_mul_f32_e32 v55, 0xbfb8aa3b, v55
	v_mul_f32_e32 v59, 0xbfb8aa3b, v59
	v_exp_f32_e32 v54, v54
	v_add_f32_e32 v58, 1.0, v62
	v_add_f32_e32 v62, 1.0, v66
	v_exp_f32_e32 v55, v55
	v_exp_f32_e32 v66, v59
	v_add_f32_e32 v59, 1.0, v63
	v_rcp_f32_e32 v58, v58
	v_rcp_f32_e32 v59, v59
	v_fmamk_f32 v50, v50, 0x3c800000, v244
	v_fmamk_f32 v51, v51, 0x3c800000, v245
	v_med3_f32 v50, v50, s71, v172
	v_med3_f32 v51, v51, s71, v172
	v_mul_f32_e32 v50, 0xbfb8aa3b, v50
	v_mul_f32_e32 v51, 0xbfb8aa3b, v51
	v_pk_add_f32 v[54:55], v[54:55], 1.0 op_sel_hi:[1,0]
	v_exp_f32_e32 v50, v50
	v_exp_f32_e32 v51, v51
	v_rcp_f32_e32 v67, v54
	v_pk_mul_f32 v[58:59], v[58:59], v[54:55]
	v_add_f32_e32 v54, 1.0, v66
	v_rcp_f32_e32 v62, v62
	v_rcp_f32_e32 v63, v54
	v_pk_add_f32 v[50:51], v[50:51], 1.0 op_sel_hi:[1,0]
	v_rcp_f32_e32 v66, v55
	v_rcp_f32_e32 v68, v50
	v_pk_mul_f32 v[54:55], v[62:63], v[50:51]
	v_fmamk_f32 v50, v64, 0x3c800000, v234
	v_med3_f32 v50, v50, s71, v172
	v_mul_f32_e32 v50, 0xbfb8aa3b, v50
	v_rcp_f32_e32 v62, v51
	v_exp_f32_e32 v51, v50
	v_fmamk_f32 v50, v56, 0x3c800000, v238
	v_fmamk_f32 v56, v60, 0x3c800000, v242
; __device__ __forceinline__ unsigned pk_bf16(float lo, float hi) { const f32x2_t v = {lo, hi}; return __builtin_bit_cast(unsigned, __builtin_convertvector(v, bf16x2_t)); }
;     __device__ __forceinline__ bool operator()(f32x4 (&acc)[2][2][4][2], const Unit& u, int wr, int wc, int fr, int fq) const {
;     ...
;                 for (int m = 0; m < 4; ++m) { const int row = r0 + ai * HALF + m * 16;
;                     const f32x4 a0 = acc[ai][0][m][0] * gsc + ba0, a1 = acc[ai][0][m][1] * gsc + ba1, b0 = acc[ai][1][m][0] * gsc + bb0, b1 = acc[ai][1][m][1] * gsc + bb1;
;                     f32x4 r0v, r1v, s0v, s1v;
; #pragma unroll
;                     for (int j = 0; j < 4; ++j) {
;                         const float ea0 = __builtin_amdgcn_exp2f(-1.44269504f * fminf(fmaxf(a0[j], -40.f), 40.f)), eb0 = __builtin_amdgcn_exp2f(-1.44269504f * fminf(fmaxf(b0[j], -40.f), 40.f));
;                         const float ea1 = __builtin_amdgcn_exp2f(-1.44269504f * fminf(fmaxf(a1[j], -40.f), 40.f)), eb1 = __builtin_amdgcn_exp2f(-1.44269504f * fminf(fmaxf(b1[j], -40.f), 40.f));
;                         s0v[j] = __builtin_amdgcn_rcpf(1.0f + eb0); s1v[j] = __builtin_amdgcn_rcpf(1.0f + eb1);
;                         r0v[j] = (1.0f + eb0) * __builtin_amdgcn_rcpf(1.0f + ea0); r1v[j] = (1.0f + eb1) * __builtin_amdgcn_rcpf(1.0f + ea1); }
;                     u32x4 w; w.x = pk_bf16(r0v[0], r0v[1]); w.y = pk_bf16(r0v[2], r0v[3]); w.z = pk_bf16(r1v[0], r1v[1]); w.w = pk_bf16(r1v[2], r1v[3]);
;                     *(u32x4*)(SGR + (size_t)row * D + ch0) = w;
;                     w.x = pk_bf16(s0v[0], s0v[1]); w.y = pk_bf16(s0v[2], s0v[3]); w.z = pk_bf16(s1v[0], s1v[1]); w.w = pk_bf16(s1v[2], s1v[3]);
;                     *(u32x4*)(SGB + (size_t)row * D + ch0) = w; }
	v_med3_f32 v56, v56, s71, v172
	v_mul_f32_e32 v56, 0xbfb8aa3b, v56
	v_exp_f32_e32 v60, v56
	v_add_f32_e32 v51, 1.0, v51
	v_rcp_f32_e32 v56, v51
	v_med3_f32 v50, v50, s71, v172
	v_add_f32_e32 v51, 1.0, v60
	v_rcp_f32_e32 v60, v51
	v_fmamk_f32 v51, v65, 0x3c800000, v235
	v_med3_f32 v51, v51, s71, v172
	v_mul_f32_e32 v51, 0xbfb8aa3b, v51
	v_exp_f32_e32 v63, v51
	v_fmamk_f32 v51, v57, 0x3c800000, v239
	v_fmamk_f32 v57, v61, 0x3c800000, v243
	v_med3_f32 v51, v51, s71, v172
	v_med3_f32 v57, v57, s71, v172
	v_mul_f32_e32 v50, 0xbfb8aa3b, v50
	v_mul_f32_e32 v51, 0xbfb8aa3b, v51
	v_mul_f32_e32 v57, 0xbfb8aa3b, v57
	v_exp_f32_e32 v50, v50
	v_fmamk_f32 v52, v52, 0x3c800000, v246
	v_exp_f32_e32 v51, v51
	v_exp_f32_e32 v61, v57
	v_fmamk_f32 v53, v53, 0x3c800000, v247
	v_add_f32_e32 v57, 1.0, v63
	v_med3_f32 v52, v52, s71, v172
	v_med3_f32 v53, v53, s71, v172
	v_rcp_f32_e32 v57, v57
	v_mul_f32_e32 v52, 0xbfb8aa3b, v52
	v_mul_f32_e32 v53, 0xbfb8aa3b, v53
	v_exp_f32_e32 v52, v52
	v_exp_f32_e32 v53, v53
	v_pk_add_f32 v[50:51], v[50:51], 1.0 op_sel_hi:[1,0]
	v_fmamk_f32 v46, v46, 0x3c800000, v232
	v_rcp_f32_e32 v63, v50
	v_pk_mul_f32 v[56:57], v[56:57], v[50:51]
	v_add_f32_e32 v50, 1.0, v61
	v_rcp_f32_e32 v61, v50
	v_rcp_f32_e32 v64, v51
	v_pk_add_f32 v[50:51], v[52:53], 1.0 op_sel_hi:[1,0]
	v_cvt_pk_bf16_f32 v52, v54, v55
	v_rcp_f32_e32 v65, v50
	v_rcp_f32_e32 v69, v51
	v_lshl_add_u64 v[54:55], v[132:133], 0, s[20:21]
	v_pk_mul_f32 v[60:61], v[60:61], v[50:51]
	v_cvt_pk_bf16_f32 v51, v56, v57
	v_lshl_add_u64 v[56:57], s[4:5], 0, v[54:55]
	v_fmamk_f32 v42, v42, 0x3c800000, v240
	v_fmamk_f32 v47, v47, 0x3c800000, v233
	v_cvt_pk_bf16_f32 v50, v58, v59
	v_cvt_pk_bf16_f32 v53, v60, v61
	v_lshl_add_u64 v[56:57], v[56:57], 0, v[130:131]
	v_lshl_add_u64 v[54:55], s[14:15], 0, v[54:55]
	v_med3_f32 v46, v46, s71, v172
	v_med3_f32 v42, v42, s71, v172
	v_med3_f32 v47, v47, s71, v172
	s_cbranch_vccnz .Lwt_p1b_11
	global_store_dwordx4 v[56:57], v[50:53], off
.Lj_p1b_11:
	v_lshl_add_u64 v[54:55], v[54:55], 0, v[130:131]
	v_mul_f32_e32 v46, 0xbfb8aa3b, v46
	v_cvt_pk_bf16_f32 v50, v67, v66
	v_cvt_pk_bf16_f32 v51, v63, v64
	v_cvt_pk_bf16_f32 v52, v68, v62
	v_cvt_pk_bf16_f32 v53, v65, v69
	v_mul_f32_e32 v42, 0xbfb8aa3b, v42
	v_mul_f32_e32 v47, 0xbfb8aa3b, v47
	s_cbranch_vccnz .Lwt_p1b_12
	global_store_dwordx4 v[54:55], v[50:53], off
.Lj_p1b_12:
	v_exp_f32_e32 v46, v46
	v_exp_f32_e32 v47, v47
	v_exp_f32_e32 v50, v42
	v_fmamk_f32 v14, v30, 0x3c800000, v232
	v_fmamk_f32 v15, v31, 0x3c800000, v233
	v_fmamk_f32 v38, v38, 0x3c800000, v236
	v_fmamk_f32 v39, v39, 0x3c800000, v237
	v_fmamk_f32 v43, v43, 0x3c800000, v241
	v_med3_f32 v14, v14, s71, v172
	v_med3_f32 v15, v15, s71, v172
	v_med3_f32 v38, v38, s71, v172
	v_med3_f32 v39, v39, s71, v172
	v_med3_f32 v43, v43, s71, v172
	v_mul_f32_e32 v14, 0xbfb8aa3b, v14
	v_mul_f32_e32 v15, 0xbfb8aa3b, v15
	v_mul_f32_e32 v38, 0xbfb8aa3b, v38
	v_mul_f32_e32 v39, 0xbfb8aa3b, v39
	v_mul_f32_e32 v43, 0xbfb8aa3b, v43
	v_exp_f32_e32 v14, v14
	v_exp_f32_e32 v15, v15
	v_exp_f32_e32 v38, v38
	v_add_f32_e32 v42, 1.0, v46
	v_add_f32_e32 v46, 1.0, v50
	v_exp_f32_e32 v39, v39
	v_exp_f32_e32 v50, v43
	v_add_f32_e32 v43, 1.0, v47
	v_fmamk_f32 v10, v22, 0x3c800000, v236
	v_fmamk_f32 v6, v26, 0x3c800000, v240
	v_fmamk_f32 v11, v23, 0x3c800000, v237
	v_fmamk_f32 v7, v27, 0x3c800000, v241
	v_rcp_f32_e32 v42, v42
	v_rcp_f32_e32 v43, v43
	v_med3_f32 v10, v10, s71, v172
	v_med3_f32 v6, v6, s71, v172
	v_med3_f32 v11, v11, s71, v172
	v_med3_f32 v7, v7, s71, v172
	v_fmamk_f32 v34, v34, 0x3c800000, v244
	v_fmamk_f32 v35, v35, 0x3c800000, v245
	v_mul_f32_e32 v10, 0xbfb8aa3b, v10
	v_mul_f32_e32 v6, 0xbfb8aa3b, v6
	v_mul_f32_e32 v11, 0xbfb8aa3b, v11
	v_mul_f32_e32 v7, 0xbfb8aa3b, v7
	v_med3_f32 v34, v34, s71, v172
	v_med3_f32 v35, v35, s71, v172
	v_exp_f32_e32 v10, v10
	v_exp_f32_e32 v22, v6
	v_fmamk_f32 v2, v18, 0x3c800000, v244
	v_add_f32_e32 v6, 1.0, v14
	v_exp_f32_e32 v11, v11
	v_exp_f32_e32 v18, v7
	v_add_f32_e32 v7, 1.0, v15
	v_mul_f32_e32 v34, 0xbfb8aa3b, v34
	v_mul_f32_e32 v35, 0xbfb8aa3b, v35
	v_pk_add_f32 v[38:39], v[38:39], 1.0 op_sel_hi:[1,0]
	v_rcp_f32_e32 v6, v6
	v_rcp_f32_e32 v7, v7
	v_exp_f32_e32 v34, v34
	v_exp_f32_e32 v35, v35
	v_rcp_f32_e32 v51, v38
	v_pk_mul_f32 v[42:43], v[42:43], v[38:39]
	v_add_f32_e32 v38, 1.0, v50
	v_fmamk_f32 v3, v19, 0x3c800000, v245
	v_rcp_f32_e32 v46, v46
	v_rcp_f32_e32 v47, v38
	v_med3_f32 v2, v2, s71, v172
	v_med3_f32 v3, v3, s71, v172
	v_mul_f32_e32 v2, 0xbfb8aa3b, v2
	v_mul_f32_e32 v3, 0xbfb8aa3b, v3
	v_pk_add_f32 v[10:11], v[10:11], 1.0 op_sel_hi:[1,0]
	v_exp_f32_e32 v2, v2
	v_add_f32_e32 v14, 1.0, v22
	v_exp_f32_e32 v3, v3
	v_rcp_f32_e32 v19, v10
	v_pk_mul_f32 v[6:7], v[6:7], v[10:11]
	v_add_f32_e32 v10, 1.0, v18
	v_pk_add_f32 v[34:35], v[34:35], 1.0 op_sel_hi:[1,0]
; __device__ __forceinline__ unsigned pk_bf16(float lo, float hi) { const f32x2_t v = {lo, hi}; return __builtin_bit_cast(unsigned, __builtin_convertvector(v, bf16x2_t)); }
; template <int MODE  , class Epi, class Sched>
; __device__ __forceinline__ void gemm_phase(LAS unsigned char* lds, const GemmDesc g, const Sched& S, const Epi& E) {
;     ...
;         if (!has_next) break;
;     __device__ __forceinline__ bool operator()(f32x4 (&acc)[2][2][4][2], const Unit& u, int wr, int wc, int fr, int fq) const {
;     ...
;                 for (int m = 0; m < 4; ++m) { const int row = r0 + ai * HALF + m * 16;
;                     const f32x4 a0 = acc[ai][0][m][0] * gsc + ba0, a1 = acc[ai][0][m][1] * gsc + ba1, b0 = acc[ai][1][m][0] * gsc + bb0, b1 = acc[ai][1][m][1] * gsc + bb1;
;                     f32x4 r0v, r1v, s0v, s1v;
; #pragma unroll
;                     for (int j = 0; j < 4; ++j) {
;                         const float ea0 = __builtin_amdgcn_exp2f(-1.44269504f * fminf(fmaxf(a0[j], -40.f), 40.f)), eb0 = __builtin_amdgcn_exp2f(-1.44269504f * fminf(fmaxf(b0[j], -40.f), 40.f));
;                         const float ea1 = __builtin_amdgcn_exp2f(-1.44269504f * fminf(fmaxf(a1[j], -40.f), 40.f)), eb1 = __builtin_amdgcn_exp2f(-1.44269504f * fminf(fmaxf(b1[j], -40.f), 40.f));
;                         s0v[j] = __builtin_amdgcn_rcpf(1.0f + eb0); s1v[j] = __builtin_amdgcn_rcpf(1.0f + eb1);
;                         r0v[j] = (1.0f + eb0) * __builtin_amdgcn_rcpf(1.0f + ea0); r1v[j] = (1.0f + eb1) * __builtin_amdgcn_rcpf(1.0f + ea1); }
;                     u32x4 w; w.x = pk_bf16(r0v[0], r0v[1]); w.y = pk_bf16(r0v[2], r0v[3]); w.z = pk_bf16(r1v[0], r1v[1]); w.w = pk_bf16(r1v[2], r1v[3]);
;                     *(u32x4*)(SGR + (size_t)row * D + ch0) = w;
;                     w.x = pk_bf16(s0v[0], s0v[1]); w.y = pk_bf16(s0v[2], s0v[3]); w.z = pk_bf16(s1v[0], s1v[1]); w.w = pk_bf16(s1v[2], s1v[3]);
;                     *(u32x4*)(SGB + (size_t)row * D + ch0) = w; }
	v_rcp_f32_e32 v14, v14
	v_rcp_f32_e32 v15, v10
	v_rcp_f32_e32 v50, v39
	v_rcp_f32_e32 v52, v34
	v_pk_mul_f32 v[38:39], v[46:47], v[34:35]
	v_fmamk_f32 v34, v48, 0x3c800000, v234
	v_med3_f32 v34, v34, s71, v172
	v_mul_f32_e32 v34, 0xbfb8aa3b, v34
	v_pk_add_f32 v[2:3], v[2:3], 1.0 op_sel_hi:[1,0]
	v_rcp_f32_e32 v46, v35
	v_exp_f32_e32 v35, v34
	v_fmamk_f32 v34, v40, 0x3c800000, v238
	v_fmamk_f32 v40, v44, 0x3c800000, v242
	v_rcp_f32_e32 v18, v11
	v_rcp_f32_e32 v22, v2
	v_pk_mul_f32 v[10:11], v[14:15], v[2:3]
	v_fmamk_f32 v2, v32, 0x3c800000, v234
	v_med3_f32 v40, v40, s71, v172
	v_med3_f32 v2, v2, s71, v172
	v_fmamk_f32 v8, v28, 0x3c800000, v242
	v_mul_f32_e32 v40, 0xbfb8aa3b, v40
	v_mul_f32_e32 v2, 0xbfb8aa3b, v2
	v_med3_f32 v8, v8, s71, v172
	v_exp_f32_e32 v44, v40
	v_rcp_f32_e32 v14, v3
	v_exp_f32_e32 v3, v2
	v_mul_f32_e32 v8, 0xbfb8aa3b, v8
	v_fmamk_f32 v2, v24, 0x3c800000, v238
	v_exp_f32_e32 v12, v8
	v_add_f32_e32 v35, 1.0, v35
	v_rcp_f32_e32 v40, v35
	v_add_f32_e32 v35, 1.0, v44
	v_add_f32_e32 v3, 1.0, v3
	v_rcp_f32_e32 v44, v35
	v_fmamk_f32 v35, v49, 0x3c800000, v235
	v_rcp_f32_e32 v8, v3
	v_add_f32_e32 v3, 1.0, v12
	v_fmamk_f32 v17, v33, 0x3c800000, v235
	v_rcp_f32_e32 v12, v3
	v_med3_f32 v3, v17, s71, v172
	v_med3_f32 v35, v35, s71, v172
	v_mul_f32_e32 v3, 0xbfb8aa3b, v3
	v_mul_f32_e32 v35, 0xbfb8aa3b, v35
	v_exp_f32_e32 v15, v3
	v_exp_f32_e32 v47, v35
	v_fmamk_f32 v35, v41, 0x3c800000, v239
	v_fmamk_f32 v41, v45, 0x3c800000, v243
	v_fmamk_f32 v13, v25, 0x3c800000, v239
	v_fmamk_f32 v9, v29, 0x3c800000, v243
	v_med3_f32 v2, v2, s71, v172
	v_med3_f32 v3, v13, s71, v172
	v_med3_f32 v9, v9, s71, v172
	v_med3_f32 v34, v34, s71, v172
	v_med3_f32 v35, v35, s71, v172
	v_med3_f32 v41, v41, s71, v172
	v_mul_f32_e32 v2, 0xbfb8aa3b, v2
	v_mul_f32_e32 v3, 0xbfb8aa3b, v3
	v_mul_f32_e32 v9, 0xbfb8aa3b, v9
	v_mul_f32_e32 v34, 0xbfb8aa3b, v34
	v_mul_f32_e32 v35, 0xbfb8aa3b, v35
	v_mul_f32_e32 v41, 0xbfb8aa3b, v41
	v_exp_f32_e32 v2, v2
	v_exp_f32_e32 v3, v3
	v_exp_f32_e32 v13, v9
	v_add_f32_e32 v9, 1.0, v15
	v_exp_f32_e32 v34, v34
	v_fmamk_f32 v36, v36, 0x3c800000, v246
	v_exp_f32_e32 v35, v35
	v_exp_f32_e32 v45, v41
	v_fmamk_f32 v37, v37, 0x3c800000, v247
	v_add_f32_e32 v41, 1.0, v47
	v_fmamk_f32 v4, v20, 0x3c800000, v246
	v_fmamk_f32 v5, v21, 0x3c800000, v247
	v_rcp_f32_e32 v9, v9
	v_med3_f32 v36, v36, s71, v172
	v_med3_f32 v37, v37, s71, v172
	v_rcp_f32_e32 v41, v41
	v_med3_f32 v4, v4, s71, v172
	v_med3_f32 v5, v5, s71, v172
	v_mul_f32_e32 v36, 0xbfb8aa3b, v36
	v_mul_f32_e32 v37, 0xbfb8aa3b, v37
	v_mul_f32_e32 v4, 0xbfb8aa3b, v4
	v_mul_f32_e32 v5, 0xbfb8aa3b, v5
	v_exp_f32_e32 v36, v36
	v_exp_f32_e32 v37, v37
	v_exp_f32_e32 v4, v4
	v_exp_f32_e32 v5, v5
	v_pk_add_f32 v[2:3], v[2:3], 1.0 op_sel_hi:[1,0]
	v_pk_add_f32 v[34:35], v[34:35], 1.0 op_sel_hi:[1,0]
	v_rcp_f32_e32 v15, v2
	v_pk_mul_f32 v[8:9], v[8:9], v[2:3]
	v_add_f32_e32 v2, 1.0, v13
	v_rcp_f32_e32 v47, v34
	v_pk_mul_f32 v[40:41], v[40:41], v[34:35]
	v_add_f32_e32 v34, 1.0, v45
	v_rcp_f32_e32 v13, v2
	v_rcp_f32_e32 v45, v34
	v_rcp_f32_e32 v48, v35
	v_pk_add_f32 v[34:35], v[36:37], 1.0 op_sel_hi:[1,0]
	v_rcp_f32_e32 v16, v3
	v_pk_add_f32 v[2:3], v[4:5], 1.0 op_sel_hi:[1,0]
	v_rcp_f32_e32 v49, v34
	v_rcp_f32_e32 v53, v35
	v_rcp_f32_e32 v17, v2
	v_rcp_f32_e32 v20, v3
	v_cvt_pk_bf16_f32 v36, v38, v39
	v_lshl_add_u64 v[38:39], v[132:133], 0, s[34:35]
	v_pk_mul_f32 v[12:13], v[12:13], v[2:3]
	v_cvt_pk_bf16_f32 v2, v6, v7
	v_lshl_add_u64 v[6:7], v[132:133], 0, s[40:41]
	v_pk_mul_f32 v[44:45], v[44:45], v[34:35]
	v_cvt_pk_bf16_f32 v35, v40, v41
	v_lshl_add_u64 v[40:41], s[4:5], 0, v[38:39]
	v_cvt_pk_bf16_f32 v3, v8, v9
	v_lshl_add_u64 v[8:9], s[4:5], 0, v[6:7]
	v_cvt_pk_bf16_f32 v34, v42, v43
	v_cvt_pk_bf16_f32 v37, v44, v45
	v_lshl_add_u64 v[40:41], v[40:41], 0, v[130:131]
	v_lshl_add_u64 v[38:39], s[14:15], 0, v[38:39]
	v_cvt_pk_bf16_f32 v4, v10, v11
	v_cvt_pk_bf16_f32 v5, v12, v13
	v_lshl_add_u64 v[8:9], v[8:9], 0, v[130:131]
	v_lshl_add_u64 v[6:7], s[14:15], 0, v[6:7]
	s_cbranch_vccnz .Lwt_p1b_13
	global_store_dwordx4 v[40:41], v[34:37], off
.Lj_p1b_13:
	v_lshl_add_u64 v[38:39], v[38:39], 0, v[130:131]
	s_cbranch_vccnz .Lwt_p1b_14
	global_store_dwordx4 v[8:9], v[2:5], off
.Lj_p1b_14:
	v_cvt_pk_bf16_f32 v34, v51, v50
	v_cvt_pk_bf16_f32 v35, v47, v48
	v_cvt_pk_bf16_f32 v36, v52, v46
	v_cvt_pk_bf16_f32 v37, v49, v53
	v_cvt_pk_bf16_f32 v2, v19, v18
	v_cvt_pk_bf16_f32 v3, v15, v16
	v_cvt_pk_bf16_f32 v4, v22, v14
	v_cvt_pk_bf16_f32 v5, v17, v20
	v_lshl_add_u64 v[6:7], v[6:7], 0, v[130:131]
	s_cbranch_vccnz .Lwt_p1b_15
	global_store_dwordx4 v[38:39], v[34:37], off
.Lj_p1b_15:
	s_cbranch_vccnz .Lwt_p1b_16
	global_store_dwordx4 v[6:7], v[2:5], off
.Lj_p1b_16:
	s_cbranch_vccz .LBB0_730
	s_cmp_eq_u32 s101, 1
	s_cbranch_scc0 .Lnodx_p1b
	s_barrier
	s_mov_b32 s101, 0

; __device__ __forceinline__ unsigned pk_bf16(float lo, float hi) { const f32x2_t v = {lo, hi}; return __builtin_bit_cast(unsigned, __builtin_convertvector(v, bf16x2_t)); }
;     __device__ __forceinline__ bool operator()(f32x4 (&acc)[2][2][4][2], const Unit& u, int wr, int wc, int fr, int fq) const {
;     ...
;                 for (int bj = 0; bj < 2; ++bj) { const f32x4 v0 = acc[ai][bj][m][0], v1 = acc[ai][bj][m][1];
;                     u32x4 w; w.x = pk_bf16(v0[0], v0[1]); w.y = pk_bf16(v0[2], v0[3]); w.z = pk_bf16(v1[0], v1[1]); w.w = pk_bf16(v1[2], v1[3]);
;                     *(u32x4*)(MG + off + bj * HALF) = w; } }
.Lwt_sa_1:
	global_store_dwordx4 v[136:137], v[130:133], off sc1
	s_branch .Lj_sa_1
.Lwt_sa_2:
	global_store_dwordx4 v[136:137], v[130:133], off offset:256 sc1
	s_branch .Lj_sa_2

; __device__ __forceinline__ unsigned pk_bf16(float lo, float hi) { const f32x2_t v = {lo, hi}; return __builtin_bit_cast(unsigned, __builtin_convertvector(v, bf16x2_t)); }
;     __device__ __forceinline__ bool operator()(f32x4 (&acc)[2][2][4][2], const Unit& u, int wr, int wc, int fr, int fq) const {
;     ...
;                 for (int bj = 0; bj < 2; ++bj) { const f32x4 v0 = acc[ai][bj][m][0], v1 = acc[ai][bj][m][1];
;                     u32x4 w; w.x = pk_bf16(v0[0], v0[1]); w.y = pk_bf16(v0[2], v0[3]); w.z = pk_bf16(v1[0], v1[1]); w.w = pk_bf16(v1[2], v1[3]);
;                     *(u32x4*)(MG + off + bj * HALF) = w; } }
.Lwt_sa_15:
	global_store_dwordx4 v[134:135], v[130:133], off sc1
	s_branch .Lj_sa_15
.Lwt_sa_16:
	global_store_dwordx4 v[134:135], v[130:133], off offset:256 sc1
	s_branch .Lj_sa_16

; __device__ __forceinline__ float bf_lo(unsigned w) { return __uint_as_float(w << 16); }
; __device__ __forceinline__ float bf_hi(unsigned w) { return __uint_as_float(w & 0xffff0000u); }
;     __device__ __forceinline__ bool operator()(f32x4 (&acc)[2][2][4][2], const Unit& u, int wr, int wc, int fr, int fq) const {
;         const int r0 = u.pm * BM + wr * 64 + fr, c0 = u.pn * BM + wc * 32 + fq * 8;
;         const bf16_t* S = u.kh ? SGB : SGR;
; #pragma unroll
;         for (int ai = 0; ai < 2; ++ai)
; #pragma unroll
;             for (int m = 0; m < 4; ++m) { const size_t off = (size_t)(r0 + ai * HALF + m * 16) * D + c0;
; #pragma unroll
;                 for (int bj = 0; bj < 2; ++bj) { const u32x4 s = *(const u32x4*)(S + off + bj * HALF);
;                     f32x4 v0 = acc[ai][bj][m][0], v1 = acc[ai][bj][m][1];
;                     v0[0] *= bf_lo(s.x); v0[1] *= bf_hi(s.x); v0[2] *= bf_lo(s.y); v0[3] *= bf_hi(s.y);
;                     v1[0] *= bf_lo(s.z); v1[1] *= bf_hi(s.z); v1[2] *= bf_lo(s.w); v1[3] *= bf_hi(s.w);
;                     acc[ai][bj][m][0] = v0; acc[ai][bj][m][1] = v1; } }
.Lkepi_sa:
	s_cmp_lg_u32 s65, 0
	s_cselect_b64 s[42:43], -1, 0
	s_cmp_eq_u32 s65, 0
	s_cselect_b64 s[0:1], -1, 0
	s_and_b64 vcc, s[0:1], exec
	v_lshl_add_u32 v160, s64, 8, v1
	v_lshl_or_b32 v158, s66, 8, v173
	s_cselect_b32 s0, s5, s15
	s_cselect_b32 s1, s4, s14
	v_mov_b32_e32 v130, s1
	v_mov_b32_e32 v131, s0
	v_ashrrev_i32_e32 v159, 31, v158
	v_ashrrev_i32_e32 v161, 31, v160
	v_lshl_add_u64 v[170:171], v[158:159], 1, v[130:131]
	v_lshlrev_b64 v[130:131], 12, v[160:161]
	v_or_b32_e32 v162, 16, v160
	v_lshl_add_u64 v[130:131], v[170:171], 0, v[130:131]
	v_ashrrev_i32_e32 v163, 31, v162
	v_mov_b64_e32 v[228:229], v[130:131]
	global_load_dwordx4 v[142:145], v[130:131], off
	global_load_dwordx4 v[176:179], v[130:131], off offset:256
	v_lshlrev_b64 v[130:131], 12, v[162:163]
	v_or_b32_e32 v164, 32, v160
	v_lshl_add_u64 v[130:131], v[170:171], 0, v[130:131]
	v_ashrrev_i32_e32 v165, 31, v164
	global_load_dwordx4 v[180:183], v[130:131], off
	global_load_dwordx4 v[184:187], v[130:131], off offset:256
	v_lshlrev_b64 v[130:131], 12, v[164:165]
	v_lshl_add_u64 v[130:131], v[170:171], 0, v[130:131]
	global_load_dwordx4 v[192:195], v[130:131], off
	global_load_dwordx4 v[196:199], v[130:131], off offset:256
	v_or_b32_e32 v166, 48, v160
	v_add_u32_e32 v168, 0x80, v160
	v_ashrrev_i32_e32 v167, 31, v166
	v_ashrrev_i32_e32 v169, 31, v168
	v_lshlrev_b64 v[130:131], 12, v[166:167]
	v_lshlrev_b64 v[132:133], 12, v[168:169]
	v_lshl_add_u64 v[130:131], v[170:171], 0, v[130:131]
	v_lshl_add_u64 v[134:135], v[170:171], 0, v[132:133]
	global_load_dwordx4 v[200:203], v[130:131], off
	global_load_dwordx4 v[138:141], v[130:131], off offset:256
	s_nop 0
	global_load_dwordx4 v[130:133], v[134:135], off
	s_nop 0
	global_load_dwordx4 v[134:137], v[134:135], off offset:256
	s_mov_b64 s[0:1], 0x90000
	v_lshl_add_u64 v[226:227], v[228:229], 0, s[0:1]
	global_load_dwordx4 v[232:235], v[226:227], off
	global_load_dwordx4 v[236:239], v[226:227], off offset:256
	s_mov_b64 s[0:1], 0xa0000
	v_lshl_add_u64 v[226:227], v[228:229], 0, s[0:1]
	global_load_dwordx4 v[240:243], v[226:227], off
	global_load_dwordx4 v[244:247], v[226:227], off offset:256
	s_mov_b64 s[0:1], 0xb0000
	v_lshl_add_u64 v[226:227], v[228:229], 0, s[0:1]
	global_load_dwordx4 v[248:251], v[226:227], off
	global_load_dwordx4 v[252:255], v[226:227], off offset:256
	s_waitcnt vmcnt(0)
	v_lshlrev_b32_e32 v188, 16, v142
	v_and_b32_e32 v189, 0xffff0000, v142
	v_lshlrev_b32_e32 v142, 16, v143
	v_and_b32_e32 v143, 0xffff0000, v143
	v_pk_mul_f32 v[128:129], v[128:129], v[142:143]
	v_lshlrev_b32_e32 v204, 16, v144
	v_and_b32_e32 v205, 0xffff0000, v144
	v_lshlrev_b32_e32 v144, 16, v145
	v_lshlrev_b32_e32 v142, 16, v192
	v_and_b32_e32 v143, 0xffff0000, v192
	v_pk_mul_f32 v[110:111], v[110:111], v[142:143]
	v_lshlrev_b32_e32 v142, 16, v193
	v_and_b32_e32 v143, 0xffff0000, v193
	v_pk_mul_f32 v[112:113], v[112:113], v[142:143]
	v_add_u32_e32 v142, 0x90, v160
	v_and_b32_e32 v145, 0xffff0000, v145
	v_ashrrev_i32_e32 v143, 31, v142
	v_lshlrev_b32_e32 v210, 16, v180
	v_and_b32_e32 v211, 0xffff0000, v180
	v_lshlrev_b32_e32 v180, 16, v181
	v_and_b32_e32 v181, 0xffff0000, v181
	v_pk_mul_f32 v[124:125], v[124:125], v[144:145]
	v_lshlrev_b64 v[144:145], 12, v[142:143]
	v_lshlrev_b32_e32 v206, 16, v176
	v_and_b32_e32 v207, 0xffff0000, v176
	v_lshlrev_b32_e32 v176, 16, v177
	v_and_b32_e32 v177, 0xffff0000, v177
	v_lshlrev_b32_e32 v208, 16, v178
	v_and_b32_e32 v209, 0xffff0000, v178
	v_lshlrev_b32_e32 v178, 16, v179
	v_and_b32_e32 v179, 0xffff0000, v179
	v_pk_mul_f32 v[120:121], v[120:121], v[180:181]
	v_lshl_add_u64 v[144:145], v[170:171], 0, v[144:145]
	v_lshlrev_b32_e32 v180, 16, v194
	v_and_b32_e32 v181, 0xffff0000, v194
	v_pk_mul_f32 v[96:97], v[96:97], v[176:177]
	v_pk_mul_f32 v[92:93], v[92:93], v[178:179]
	v_mov_b64_e32 v[176:177], v[232:233]
	v_mov_b64_e32 v[178:179], v[234:235]
	v_pk_mul_f32 v[106:107], v[106:107], v[180:181]
	v_lshlrev_b32_e32 v180, 16, v195
	v_and_b32_e32 v181, 0xffff0000, v195
	v_lshlrev_b32_e32 v212, 16, v182
	v_and_b32_e32 v213, 0xffff0000, v182
	v_lshlrev_b32_e32 v182, 16, v183
	v_and_b32_e32 v183, 0xffff0000, v183
	v_pk_mul_f32 v[108:109], v[108:109], v[180:181]
	v_lshlrev_b32_e32 v180, 16, v196
	v_and_b32_e32 v181, 0xffff0000, v196
	v_pk_mul_f32 v[116:117], v[116:117], v[182:183]
	v_pk_mul_f32 v[78:79], v[78:79], v[180:181]
	v_mov_b64_e32 v[180:181], v[236:237]
	v_mov_b64_e32 v[182:183], v[238:239]
	v_lshlrev_b32_e32 v144, 16, v198
	v_and_b32_e32 v145, 0xffff0000, v198
	v_pk_mul_f32 v[74:75], v[74:75], v[144:145]
	v_lshlrev_b32_e32 v144, 16, v199
	v_and_b32_e32 v145, 0xffff0000, v199
	v_lshlrev_b32_e32 v214, 16, v184
	v_and_b32_e32 v215, 0xffff0000, v184
	v_lshlrev_b32_e32 v184, 16, v185
	v_and_b32_e32 v185, 0xffff0000, v185
	v_pk_mul_f32 v[76:77], v[76:77], v[144:145]
	v_add_u32_e32 v144, 0xa0, v160
	v_pk_mul_f32 v[88:89], v[88:89], v[184:185]
	v_lshlrev_b32_e32 v184, 16, v197
	v_and_b32_e32 v185, 0xffff0000, v197
	v_ashrrev_i32_e32 v145, 31, v144
	v_pk_mul_f32 v[80:81], v[80:81], v[184:185]
	v_lshlrev_b64 v[184:185], 12, v[144:145]
	v_lshlrev_b32_e32 v216, 16, v186
	v_and_b32_e32 v217, 0xffff0000, v186
	v_lshlrev_b32_e32 v186, 16, v187
	v_and_b32_e32 v187, 0xffff0000, v187
	v_pk_mul_f32 v[126:127], v[126:127], v[188:189]
	v_lshl_add_u64 v[188:189], v[170:171], 0, v[184:185]
	v_pk_mul_f32 v[84:85], v[84:85], v[186:187]
	v_mov_b64_e32 v[184:185], v[240:241]
	v_mov_b64_e32 v[186:187], v[242:243]
	v_lshlrev_b32_e32 v192, 16, v200
	v_and_b32_e32 v193, 0xffff0000, v200
	v_pk_mul_f32 v[102:103], v[102:103], v[192:193]
	v_lshlrev_b32_e32 v192, 16, v201
	v_and_b32_e32 v193, 0xffff0000, v201
; __device__ __forceinline__ unsigned pk_bf16(float lo, float hi) { const f32x2_t v = {lo, hi}; return __builtin_bit_cast(unsigned, __builtin_convertvector(v, bf16x2_t)); }
; __device__ __forceinline__ float bf_lo(unsigned w) { return __uint_as_float(w << 16); }
; __device__ __forceinline__ float bf_hi(unsigned w) { return __uint_as_float(w & 0xffff0000u); }
;     __device__ __forceinline__ bool operator()(f32x4 (&acc)[2][2][4][2], const Unit& u, int wr, int wc, int fr, int fq) const {
;     ...
;             for (int m = 0; m < 4; ++m) { const size_t off = (size_t)(r0 + ai * HALF + m * 16) * D + c0;
; #pragma unroll
;                 for (int bj = 0; bj < 2; ++bj) { const u32x4 s = *(const u32x4*)(S + off + bj * HALF);
;                     f32x4 v0 = acc[ai][bj][m][0], v1 = acc[ai][bj][m][1];
;                     v0[0] *= bf_lo(s.x); v0[1] *= bf_hi(s.x); v0[2] *= bf_lo(s.y); v0[3] *= bf_hi(s.y);
;                     v1[0] *= bf_lo(s.z); v1[1] *= bf_hi(s.z); v1[2] *= bf_lo(s.w); v1[3] *= bf_hi(s.w);
;                     acc[ai][bj][m][0] = v0; acc[ai][bj][m][1] = v1; } }
;         if (u.kh == 0) return false;
; #pragma unroll
;         for (int ai = 0; ai < 2; ++ai)
; #pragma unroll
;             for (int m = 0; m < 4; ++m) { const size_t off = (size_t)(r0 + ai * HALF + m * 16) * LDP + c0;
; #pragma unroll
;                 for (int bj = 0; bj < 2; ++bj) { const f32x4 v0 = acc[ai][bj][m][0], v1 = acc[ai][bj][m][1];
;                     u32x4 w; w.x = pk_bf16(v0[0], v0[1]); w.y = pk_bf16(v0[2], v0[3]); w.z = pk_bf16(v1[0], v1[1]); w.w = pk_bf16(v1[2], v1[3]);
;                     *(u32x4*)(MG + off + bj * HALF) = w; } }
	v_pk_mul_f32 v[104:105], v[104:105], v[192:193]
	v_lshlrev_b32_e32 v192, 16, v202
	v_and_b32_e32 v193, 0xffff0000, v202
	v_pk_mul_f32 v[98:99], v[98:99], v[192:193]
	v_mov_b64_e32 v[192:193], v[244:245]
	v_mov_b64_e32 v[194:195], v[246:247]
	v_lshlrev_b32_e32 v188, 16, v138
	v_and_b32_e32 v189, 0xffff0000, v138
	v_lshlrev_b32_e32 v138, 16, v139
	v_and_b32_e32 v139, 0xffff0000, v139
	v_pk_mul_f32 v[72:73], v[72:73], v[138:139]
	v_add_u32_e32 v138, 0xb0, v160
	v_ashrrev_i32_e32 v139, 31, v138
	v_pk_mul_f32 v[70:71], v[70:71], v[188:189]
	v_lshlrev_b64 v[188:189], 12, v[138:139]
	v_lshlrev_b32_e32 v196, 16, v203
	v_and_b32_e32 v197, 0xffff0000, v203
	v_lshl_add_u64 v[170:171], v[170:171], 0, v[188:189]
	v_pk_mul_f32 v[100:101], v[100:101], v[196:197]
	v_mov_b64_e32 v[196:197], v[248:249]
	v_mov_b64_e32 v[198:199], v[250:251]
	v_mov_b64_e32 v[200:201], v[252:253]
	v_mov_b64_e32 v[202:203], v[254:255]
	v_lshlrev_b32_e32 v188, 16, v140
	v_and_b32_e32 v189, 0xffff0000, v140
	v_lshlrev_b32_e32 v140, 16, v141
	v_and_b32_e32 v141, 0xffff0000, v141
	v_pk_mul_f32 v[68:69], v[68:69], v[140:141]
	v_lshlrev_b32_e32 v140, 16, v130
	v_and_b32_e32 v141, 0xffff0000, v130
	v_lshlrev_b32_e32 v130, 16, v131
	v_and_b32_e32 v131, 0xffff0000, v131
	v_pk_mul_f32 v[64:65], v[64:65], v[130:131]
	v_lshlrev_b32_e32 v130, 16, v132
	v_and_b32_e32 v131, 0xffff0000, v132
	v_pk_mul_f32 v[58:59], v[58:59], v[130:131]
	v_lshlrev_b32_e32 v130, 16, v133
	v_and_b32_e32 v131, 0xffff0000, v133
	v_pk_mul_f32 v[60:61], v[60:61], v[130:131]
	v_lshlrev_b32_e32 v130, 16, v134
	v_and_b32_e32 v131, 0xffff0000, v134
	v_pk_mul_f32 v[30:31], v[30:31], v[130:131]
	v_lshlrev_b32_e32 v130, 16, v135
	v_and_b32_e32 v131, 0xffff0000, v135
	v_pk_mul_f32 v[32:33], v[32:33], v[130:131]
	v_lshlrev_b32_e32 v130, 16, v136
	v_and_b32_e32 v131, 0xffff0000, v136
	v_pk_mul_f32 v[26:27], v[26:27], v[130:131]
	v_lshlrev_b32_e32 v130, 16, v137
	v_and_b32_e32 v131, 0xffff0000, v137
	v_pk_mul_f32 v[28:29], v[28:29], v[130:131]
	s_waitcnt vmcnt(0)
	v_lshlrev_b32_e32 v130, 16, v176
	v_and_b32_e32 v131, 0xffff0000, v176
	v_pk_mul_f32 v[54:55], v[54:55], v[130:131]
	v_lshlrev_b32_e32 v130, 16, v177
	v_and_b32_e32 v131, 0xffff0000, v177
	v_pk_mul_f32 v[56:57], v[56:57], v[130:131]
	v_lshlrev_b32_e32 v130, 16, v178
	v_and_b32_e32 v131, 0xffff0000, v178
	v_pk_mul_f32 v[50:51], v[50:51], v[130:131]
	v_lshlrev_b32_e32 v130, 16, v179
	v_and_b32_e32 v131, 0xffff0000, v179
	v_pk_mul_f32 v[52:53], v[52:53], v[130:131]
	v_lshlrev_b32_e32 v130, 16, v180
	v_and_b32_e32 v131, 0xffff0000, v180
	v_pk_mul_f32 v[22:23], v[22:23], v[130:131]
	v_lshlrev_b32_e32 v130, 16, v181
	v_and_b32_e32 v131, 0xffff0000, v181
	v_pk_mul_f32 v[24:25], v[24:25], v[130:131]
	v_lshlrev_b32_e32 v130, 16, v182
	v_and_b32_e32 v131, 0xffff0000, v182
	v_pk_mul_f32 v[18:19], v[18:19], v[130:131]
	v_lshlrev_b32_e32 v130, 16, v183
	v_and_b32_e32 v131, 0xffff0000, v183
	v_pk_mul_f32 v[20:21], v[20:21], v[130:131]
	v_pk_mul_f32 v[122:123], v[122:123], v[204:205]
	v_pk_mul_f32 v[94:95], v[94:95], v[206:207]
	v_lshlrev_b32_e32 v130, 16, v184
	v_and_b32_e32 v131, 0xffff0000, v184
	v_pk_mul_f32 v[46:47], v[46:47], v[130:131]
	v_lshlrev_b32_e32 v130, 16, v185
	v_and_b32_e32 v131, 0xffff0000, v185
	v_pk_mul_f32 v[48:49], v[48:49], v[130:131]
	v_lshlrev_b32_e32 v130, 16, v186
	v_and_b32_e32 v131, 0xffff0000, v186
	v_pk_mul_f32 v[42:43], v[42:43], v[130:131]
	v_lshlrev_b32_e32 v130, 16, v187
	v_and_b32_e32 v131, 0xffff0000, v187
	v_pk_mul_f32 v[44:45], v[44:45], v[130:131]
	v_lshlrev_b32_e32 v130, 16, v192
	v_and_b32_e32 v131, 0xffff0000, v192
	v_pk_mul_f32 v[14:15], v[14:15], v[130:131]
	v_lshlrev_b32_e32 v130, 16, v193
	v_and_b32_e32 v131, 0xffff0000, v193
	v_pk_mul_f32 v[16:17], v[16:17], v[130:131]
	v_lshlrev_b32_e32 v130, 16, v194
	v_and_b32_e32 v131, 0xffff0000, v194
	v_pk_mul_f32 v[10:11], v[10:11], v[130:131]
	v_lshlrev_b32_e32 v130, 16, v195
	v_and_b32_e32 v131, 0xffff0000, v195
	v_pk_mul_f32 v[12:13], v[12:13], v[130:131]
	v_lshlrev_b32_e32 v130, 16, v196
	v_and_b32_e32 v131, 0xffff0000, v196
	v_pk_mul_f32 v[38:39], v[38:39], v[130:131]
	v_lshlrev_b32_e32 v130, 16, v197
	v_and_b32_e32 v131, 0xffff0000, v197
	v_pk_mul_f32 v[40:41], v[40:41], v[130:131]
	v_lshlrev_b32_e32 v130, 16, v198
	v_and_b32_e32 v131, 0xffff0000, v198
	v_pk_mul_f32 v[34:35], v[34:35], v[130:131]
	v_lshlrev_b32_e32 v130, 16, v199
	v_and_b32_e32 v131, 0xffff0000, v199
	v_pk_mul_f32 v[36:37], v[36:37], v[130:131]
	v_lshlrev_b32_e32 v130, 16, v200
	v_and_b32_e32 v131, 0xffff0000, v200
	v_pk_mul_f32 v[6:7], v[6:7], v[130:131]
	v_lshlrev_b32_e32 v130, 16, v201
	v_and_b32_e32 v131, 0xffff0000, v201
	v_pk_mul_f32 v[8:9], v[8:9], v[130:131]
	v_lshlrev_b32_e32 v130, 16, v202
	v_and_b32_e32 v131, 0xffff0000, v202
	v_pk_mul_f32 v[2:3], v[2:3], v[130:131]
	v_lshlrev_b32_e32 v130, 16, v203
	v_and_b32_e32 v131, 0xffff0000, v203
	v_pk_mul_f32 v[90:91], v[90:91], v[208:209]
	v_pk_mul_f32 v[118:119], v[118:119], v[210:211]
	v_pk_mul_f32 v[114:115], v[114:115], v[212:213]
	v_pk_mul_f32 v[86:87], v[86:87], v[214:215]
	v_pk_mul_f32 v[82:83], v[82:83], v[216:217]
	v_pk_mul_f32 v[66:67], v[66:67], v[188:189]
	v_pk_mul_f32 v[62:63], v[62:63], v[140:141]
	v_pk_mul_f32 v[4:5], v[4:5], v[130:131]
	s_cbranch_vccnz .LBB0_818
	v_mov_b64_e32 v[134:135], s[12:13]
	v_mad_i64_i32 v[136:137], s[0:1], v160, s60, v[134:135]
	v_lshlrev_b64 v[140:141], 1, v[158:159]
	v_cvt_pk_bf16_f32 v130, v126, v127
	v_cvt_pk_bf16_f32 v131, v128, v129
	v_cvt_pk_bf16_f32 v132, v122, v123
	v_cvt_pk_bf16_f32 v133, v124, v125
	v_lshl_add_u64 v[136:137], v[136:137], 0, v[140:141]
	s_cmp_eq_u64 s[40:41], 0
	s_cbranch_scc1 .Lwt_sa_1
	global_store_dwordx4 v[136:137], v[130:133], off
; __device__ __forceinline__ unsigned pk_bf16(float lo, float hi) { const f32x2_t v = {lo, hi}; return __builtin_bit_cast(unsigned, __builtin_convertvector(v, bf16x2_t)); }
; template <int MODE  , class Epi, class Sched>
; __device__ __forceinline__ void gemm_phase(LAS unsigned char* lds, const GemmDesc g, const Sched& S, const Epi& E) {
;     ...
;         if (zero) {
; #pragma unroll
;             for (int a = 0; a < 2; ++a)
; #pragma unroll
;                 for (int b = 0; b < 2; ++b)
; #pragma unroll
;                     for (int m = 0; m < 4; ++m)
; #pragma unroll
;                         for (int n = 0; n < 2; ++n) acc[a][b][m][n] = (f32x4){0.f, 0.f, 0.f, 0.f};
;         }
;     __device__ __forceinline__ bool operator()(f32x4 (&acc)[2][2][4][2], const Unit& u, int wr, int wc, int fr, int fq) const {
;     ...
;             for (int m = 0; m < 4; ++m) { const size_t off = (size_t)(r0 + ai * HALF + m * 16) * LDP + c0;
; #pragma unroll
;                 for (int bj = 0; bj < 2; ++bj) { const f32x4 v0 = acc[ai][bj][m][0], v1 = acc[ai][bj][m][1];
;                     u32x4 w; w.x = pk_bf16(v0[0], v0[1]); w.y = pk_bf16(v0[2], v0[3]); w.z = pk_bf16(v1[0], v1[1]); w.w = pk_bf16(v1[2], v1[3]);
;                     *(u32x4*)(MG + off + bj * HALF) = w; } }
;         return true;
.Lj_sa_1:
	s_nop 1
	v_cvt_pk_bf16_f32 v130, v94, v95
	v_cvt_pk_bf16_f32 v131, v96, v97
	v_cvt_pk_bf16_f32 v132, v90, v91
	v_cvt_pk_bf16_f32 v133, v92, v93
	s_cmp_eq_u64 s[40:41], 0
	s_cbranch_scc1 .Lwt_sa_2
	global_store_dwordx4 v[136:137], v[130:133], off offset:256
.Lj_sa_2:
	v_mad_i64_i32 v[136:137], s[0:1], v162, s60, v[134:135]
	s_nop 0
	v_cvt_pk_bf16_f32 v130, v118, v119
	v_cvt_pk_bf16_f32 v131, v120, v121
	v_cvt_pk_bf16_f32 v132, v114, v115
	v_cvt_pk_bf16_f32 v133, v116, v117
	v_lshl_add_u64 v[136:137], v[136:137], 0, v[140:141]
	s_cmp_eq_u64 s[40:41], 0
	s_cbranch_scc1 .Lwt_sa_3
	global_store_dwordx4 v[136:137], v[130:133], off
.Lj_sa_3:
	s_nop 1
	v_cvt_pk_bf16_f32 v130, v86, v87
	v_cvt_pk_bf16_f32 v131, v88, v89
	v_cvt_pk_bf16_f32 v132, v82, v83
	v_cvt_pk_bf16_f32 v133, v84, v85
	s_cmp_eq_u64 s[40:41], 0
	s_cbranch_scc1 .Lwt_sa_4
	global_store_dwordx4 v[136:137], v[130:133], off offset:256
.Lj_sa_4:
	v_mad_i64_i32 v[136:137], s[0:1], v164, s60, v[134:135]
	s_nop 0
	v_cvt_pk_bf16_f32 v130, v110, v111
	v_cvt_pk_bf16_f32 v131, v112, v113
	v_cvt_pk_bf16_f32 v132, v106, v107
	v_cvt_pk_bf16_f32 v133, v108, v109
	v_lshl_add_u64 v[136:137], v[136:137], 0, v[140:141]
	s_cmp_eq_u64 s[40:41], 0
	s_cbranch_scc1 .Lwt_sa_5
	global_store_dwordx4 v[136:137], v[130:133], off
.Lj_sa_5:
	s_nop 1
	v_cvt_pk_bf16_f32 v130, v78, v79
	v_cvt_pk_bf16_f32 v131, v80, v81
	v_cvt_pk_bf16_f32 v132, v74, v75
	v_cvt_pk_bf16_f32 v133, v76, v77
	s_cmp_eq_u64 s[40:41], 0
	s_cbranch_scc1 .Lwt_sa_6
	global_store_dwordx4 v[136:137], v[130:133], off offset:256
.Lj_sa_6:
	v_mad_i64_i32 v[136:137], s[0:1], v166, s60, v[134:135]
	s_nop 0
	v_cvt_pk_bf16_f32 v130, v102, v103
	v_cvt_pk_bf16_f32 v131, v104, v105
	v_cvt_pk_bf16_f32 v132, v98, v99
	v_cvt_pk_bf16_f32 v133, v100, v101
	v_lshl_add_u64 v[136:137], v[136:137], 0, v[140:141]
	s_cmp_eq_u64 s[40:41], 0
	s_cbranch_scc1 .Lwt_sa_7
	global_store_dwordx4 v[136:137], v[130:133], off
.Lj_sa_7:
	s_nop 1
	v_cvt_pk_bf16_f32 v130, v70, v71
	v_cvt_pk_bf16_f32 v131, v72, v73
	v_cvt_pk_bf16_f32 v132, v66, v67
	v_cvt_pk_bf16_f32 v133, v68, v69
	s_cmp_eq_u64 s[40:41], 0
	s_cbranch_scc1 .Lwt_sa_8
	global_store_dwordx4 v[136:137], v[130:133], off offset:256
.Lj_sa_8:
	v_mad_i64_i32 v[136:137], s[0:1], v168, s60, v[134:135]
	s_nop 0
	v_cvt_pk_bf16_f32 v130, v62, v63
	v_cvt_pk_bf16_f32 v131, v64, v65
	v_cvt_pk_bf16_f32 v132, v58, v59
	v_cvt_pk_bf16_f32 v133, v60, v61
	v_lshl_add_u64 v[136:137], v[136:137], 0, v[140:141]
	s_cmp_eq_u64 s[40:41], 0
	s_cbranch_scc1 .Lwt_sa_9
	global_store_dwordx4 v[136:137], v[130:133], off
.Lj_sa_9:
	s_nop 1
	v_cvt_pk_bf16_f32 v130, v30, v31
	v_cvt_pk_bf16_f32 v131, v32, v33
	v_cvt_pk_bf16_f32 v132, v26, v27
	v_cvt_pk_bf16_f32 v133, v28, v29
	s_cmp_eq_u64 s[40:41], 0
	s_cbranch_scc1 .Lwt_sa_10
	global_store_dwordx4 v[136:137], v[130:133], off offset:256
.Lj_sa_10:
	v_mad_i64_i32 v[136:137], s[0:1], v142, s60, v[134:135]
	s_nop 0
	v_cvt_pk_bf16_f32 v130, v54, v55
	v_cvt_pk_bf16_f32 v131, v56, v57
	v_cvt_pk_bf16_f32 v132, v50, v51
	v_cvt_pk_bf16_f32 v133, v52, v53
	v_lshl_add_u64 v[136:137], v[136:137], 0, v[140:141]
	s_cmp_eq_u64 s[40:41], 0
	s_cbranch_scc1 .Lwt_sa_11
	global_store_dwordx4 v[136:137], v[130:133], off
.Lj_sa_11:
	s_nop 1
	v_cvt_pk_bf16_f32 v130, v22, v23
	v_cvt_pk_bf16_f32 v131, v24, v25
	v_cvt_pk_bf16_f32 v132, v18, v19
	v_cvt_pk_bf16_f32 v133, v20, v21
	s_cmp_eq_u64 s[40:41], 0
	s_cbranch_scc1 .Lwt_sa_12
	global_store_dwordx4 v[136:137], v[130:133], off offset:256
.Lj_sa_12:
	v_mad_i64_i32 v[136:137], s[0:1], v144, s60, v[134:135]
	s_nop 0
	v_cvt_pk_bf16_f32 v130, v46, v47
	v_cvt_pk_bf16_f32 v131, v48, v49
	v_cvt_pk_bf16_f32 v132, v42, v43
	v_cvt_pk_bf16_f32 v133, v44, v45
	v_lshl_add_u64 v[136:137], v[136:137], 0, v[140:141]
	s_cmp_eq_u64 s[40:41], 0
	s_cbranch_scc1 .Lwt_sa_13
	global_store_dwordx4 v[136:137], v[130:133], off
.Lj_sa_13:
	v_mad_i64_i32 v[134:135], s[0:1], v138, s60, v[134:135]
	s_nop 0
	v_cvt_pk_bf16_f32 v130, v14, v15
	v_cvt_pk_bf16_f32 v131, v16, v17
	v_cvt_pk_bf16_f32 v132, v10, v11
	v_cvt_pk_bf16_f32 v133, v12, v13
	s_cmp_eq_u64 s[40:41], 0
	s_cbranch_scc1 .Lwt_sa_14
	global_store_dwordx4 v[136:137], v[130:133], off offset:256
.Lj_sa_14:
	v_lshl_add_u64 v[134:135], v[134:135], 0, v[140:141]
	s_nop 0
	v_cvt_pk_bf16_f32 v130, v38, v39
	v_cvt_pk_bf16_f32 v131, v40, v41
	v_cvt_pk_bf16_f32 v132, v34, v35
	v_cvt_pk_bf16_f32 v133, v36, v37
	s_cmp_eq_u64 s[40:41], 0
	s_cbranch_scc1 .Lwt_sa_15
	global_store_dwordx4 v[134:135], v[130:133], off
.Lj_sa_15:
	s_nop 1
	v_cvt_pk_bf16_f32 v130, v6, v7
	v_cvt_pk_bf16_f32 v131, v8, v9
	v_cvt_pk_bf16_f32 v132, v2, v3
	v_cvt_pk_bf16_f32 v133, v4, v5
	s_cmp_eq_u64 s[40:41], 0
	s_cbranch_scc1 .Lwt_sa_16
	global_store_dwordx4 v[134:135], v[130:133], off offset:256
.Lj_sa_16:
.LBB0_818:
	s_mov_b64 s[44:45], -1
	s_and_b64 vcc, exec, s[40:41]
	s_cbranch_vccz .LBB0_803
	s_andn2_b64 vcc, exec, s[42:43]
	s_cbranch_vccnz .LBB0_802
	v_mov_b32_e32 v2, 0
	v_mov_b32_e32 v3, v2
	v_mov_b64_e32 v[4:5], v[2:3]
	v_mov_b64_e32 v[6:7], v[2:3]
	v_mov_b64_e32 v[8:9], v[2:3]
	v_mov_b64_e32 v[10:11], v[2:3]
	v_mov_b64_e32 v[12:13], v[2:3]
	v_mov_b64_e32 v[14:15], v[2:3]
	v_mov_b64_e32 v[16:17], v[2:3]
	v_mov_b64_e32 v[18:19], v[2:3]
	v_mov_b64_e32 v[20:21], v[2:3]
	v_mov_b64_e32 v[22:23], v[2:3]
	v_mov_b64_e32 v[24:25], v[2:3]
	v_mov_b64_e32 v[26:27], v[2:3]
	v_mov_b64_e32 v[28:29], v[2:3]
	v_mov_b64_e32 v[30:31], v[2:3]
	v_mov_b64_e32 v[32:33], v[2:3]
	v_mov_b64_e32 v[34:35], v[2:3]
	v_mov_b64_e32 v[36:37], v[2:3]
	v_mov_b64_e32 v[38:39], v[2:3]
	v_mov_b64_e32 v[40:41], v[2:3]
	v_mov_b64_e32 v[42:43], v[2:3]
	v_mov_b64_e32 v[44:45], v[2:3]
	v_mov_b64_e32 v[46:47], v[2:3]
	v_mov_b64_e32 v[48:49], v[2:3]
	v_mov_b64_e32 v[50:51], v[2:3]
	v_mov_b64_e32 v[52:53], v[2:3]
	v_mov_b64_e32 v[54:55], v[2:3]
	v_mov_b64_e32 v[56:57], v[2:3]
	v_mov_b64_e32 v[58:59], v[2:3]
	v_mov_b64_e32 v[60:61], v[2:3]
	v_mov_b64_e32 v[62:63], v[2:3]
	v_mov_b64_e32 v[64:65], v[2:3]
	v_mov_b64_e32 v[66:67], v[2:3]
	v_mov_b64_e32 v[68:69], v[2:3]
	v_mov_b64_e32 v[70:71], v[2:3]
	v_mov_b64_e32 v[72:73], v[2:3]
	v_mov_b64_e32 v[74:75], v[2:3]
	v_mov_b64_e32 v[76:77], v[2:3]
	v_mov_b64_e32 v[78:79], v[2:3]
	v_mov_b64_e32 v[80:81], v[2:3]
	v_mov_b64_e32 v[82:83], v[2:3]
	v_mov_b64_e32 v[84:85], v[2:3]
	v_mov_b64_e32 v[86:87], v[2:3]
	v_mov_b64_e32 v[88:89], v[2:3]
	v_mov_b64_e32 v[90:91], v[2:3]
	v_mov_b64_e32 v[92:93], v[2:3]
	v_mov_b64_e32 v[94:95], v[2:3]
	v_mov_b64_e32 v[96:97], v[2:3]
	v_mov_b64_e32 v[98:99], v[2:3]
	v_mov_b64_e32 v[100:101], v[2:3]
	v_mov_b64_e32 v[102:103], v[2:3]
	v_mov_b64_e32 v[104:105], v[2:3]
	v_mov_b64_e32 v[106:107], v[2:3]
	v_mov_b64_e32 v[108:109], v[2:3]
	v_mov_b64_e32 v[110:111], v[2:3]
	v_mov_b64_e32 v[112:113], v[2:3]
	v_mov_b64_e32 v[114:115], v[2:3]
	v_mov_b64_e32 v[116:117], v[2:3]
	v_mov_b64_e32 v[118:119], v[2:3]
	v_mov_b64_e32 v[120:121], v[2:3]
	v_mov_b64_e32 v[122:123], v[2:3]
	v_mov_b64_e32 v[124:125], v[2:3]
	v_mov_b64_e32 v[126:127], v[2:3]
	v_mov_b64_e32 v[128:129], v[2:3]
	s_branch .LBB0_802

; __device__ __forceinline__ unsigned pk_bf16(float lo, float hi) { const f32x2_t v = {lo, hi}; return __builtin_bit_cast(unsigned, __builtin_convertvector(v, bf16x2_t)); }
;     __device__ __forceinline__ bool operator()(f32x4 (&acc)[2][2][4][2], const Unit& u, int wr, int wc, int fr, int fq) const {
;     ...
;             for (int m = 0; m < 4; ++m) { bf16_t* rowp = DL + (size_t)(r0 + ai * HALF + m * 16) * LDP + c0;
; #pragma unroll
;                 for (int bj = 0; bj < 2; ++bj) { const f32x4 v0 = acc[ai][bj][m][0], v1 = acc[ai][bj][m][1];
;                     u32x4 w; w.x = pk_bf16(v0[0], v0[1]); w.y = pk_bf16(v0[2], v0[3]); w.z = pk_bf16(v1[0], v1[1]); w.w = pk_bf16(v1[2], v1[3]);
;                     *(u32x4*)(rowp + bj * HALF) = w; } }
.Lwt_sb_1:
	global_store_dwordx4 v[138:139], v[130:133], off sc1
	s_branch .Lj_sb_1
.Lwt_sb_2:
	global_store_dwordx4 v[138:139], v[130:133], off offset:256 sc1
	s_branch .Lj_sb_2

; __device__ __forceinline__ unsigned pk_bf16(float lo, float hi) { const f32x2_t v = {lo, hi}; return __builtin_bit_cast(unsigned, __builtin_convertvector(v, bf16x2_t)); }
;     __device__ __forceinline__ bool operator()(f32x4 (&acc)[2][2][4][2], const Unit& u, int wr, int wc, int fr, int fq) const {
;     ...
;             for (int m = 0; m < 4; ++m) { bf16_t* rowp = DL + (size_t)(r0 + ai * HALF + m * 16) * LDP + c0;
; #pragma unroll
;                 for (int bj = 0; bj < 2; ++bj) { const f32x4 v0 = acc[ai][bj][m][0], v1 = acc[ai][bj][m][1];
;                     u32x4 w; w.x = pk_bf16(v0[0], v0[1]); w.y = pk_bf16(v0[2], v0[3]); w.z = pk_bf16(v1[0], v1[1]); w.w = pk_bf16(v1[2], v1[3]);
;                     *(u32x4*)(rowp + bj * HALF) = w; } }
.Lwt_sb_15:
	global_store_dwordx4 v[130:131], v[132:135], off sc1
	s_branch .Lj_sb_15

; __device__ __forceinline__ unsigned pk_bf16(float lo, float hi) { const f32x2_t v = {lo, hi}; return __builtin_bit_cast(unsigned, __builtin_convertvector(v, bf16x2_t)); }
;     __device__ __forceinline__ bool operator()(f32x4 (&acc)[2][2][4][2], const Unit& u, int wr, int wc, int fr, int fq) const {
;     ...
;                 for (int bj = 0; bj < 2; ++bj) { const f32x4 v0 = acc[ai][bj][m][0], v1 = acc[ai][bj][m][1];
;                     u32x4 w; w.x = pk_bf16(v0[0], v0[1]); w.y = pk_bf16(v0[2], v0[3]); w.z = pk_bf16(v1[0], v1[1]); w.w = pk_bf16(v1[2], v1[3]);
;                     *(u32x4*)(MG + off + bj * HALF) = w; } }
;     __device__ __forceinline__ bool operator()(f32x4 (&acc)[2][2][4][2], const Unit& u, int wr, int wc, int fr, int fq) const {
;     ...
;                 for (int bj = 0; bj < 2; ++bj) { const f32x4 v0 = acc[ai][bj][m][0], v1 = acc[ai][bj][m][1];
;                     u32x4 w; w.x = pk_bf16(v0[0], v0[1]); w.y = pk_bf16(v0[2], v0[3]); w.z = pk_bf16(v1[0], v1[1]); w.w = pk_bf16(v1[2], v1[3]);
;                     *(u32x4*)(rowp + bj * HALF) = w; } }
.Lwt_sb_31:
	global_store_dwordx4 v[130:131], v[132:135], off offset:256 sc1
	s_branch .Lj_sb_31

; __device__ __forceinline__ unsigned pk_bf16(float lo, float hi) { const f32x2_t v = {lo, hi}; return __builtin_bit_cast(unsigned, __builtin_convertvector(v, bf16x2_t)); }
;     __device__ __forceinline__ bool operator()(f32x4 (&acc)[2][2][4][2], const Unit& u, int wr, int wc, int fr, int fq) const {
;         const int r0 = u.pm * BM + wr * 64 + fr, c0 = u.pn * BM + wc * 32 + fq * 8;
; #pragma unroll
;         for (int ai = 0; ai < 2; ++ai)
; #pragma unroll
;             for (int m = 0; m < 4; ++m) { bf16_t* rowp = DL + (size_t)(r0 + ai * HALF + m * 16) * LDP + c0;
; #pragma unroll
;                 for (int bj = 0; bj < 2; ++bj) { const f32x4 v0 = acc[ai][bj][m][0], v1 = acc[ai][bj][m][1];
;                     u32x4 w; w.x = pk_bf16(v0[0], v0[1]); w.y = pk_bf16(v0[2], v0[3]); w.z = pk_bf16(v1[0], v1[1]); w.w = pk_bf16(v1[2], v1[3]);
;                     *(u32x4*)(rowp + bj * HALF) = w; } }
;     __device__ __forceinline__ bool operator()(f32x4 (&acc)[2][2][4][2], const Unit& u, int wr, int wc, int fr, int fq) const {
;         if (u.type == 0) return d(acc, u, wr, wc, fr, fq);
;         if (u.kh == 0) return false;
;         return e(acc, u, wr, wc, fr, fq);
.Lkepi_sb:
	s_cmp_lg_u32 s67, 0
	s_cbranch_scc0 .LBB0_906
	s_mov_b64 s[42:43], 0
	s_cmp_lg_u32 s66, 0
	s_mov_b64 s[40:41], 0
	s_cbranch_scc0 .LBB0_901
	v_lshl_or_b32 v130, s64, 8, v175
	v_lshl_add_u32 v140, s65, 8, v1
	v_ashrrev_i32_e32 v131, 31, v130
	v_mov_b64_e32 v[134:135], s[26:27]
	v_mad_i64_i32 v[132:133], s[0:1], v140, s59, v[134:135]
	v_lshlrev_b64 v[136:137], 1, v[130:131]
	v_lshl_add_u64 v[138:139], v[132:133], 0, v[136:137]
	v_cvt_pk_bf16_f32 v130, v126, v127
	v_cvt_pk_bf16_f32 v131, v128, v129
	v_cvt_pk_bf16_f32 v132, v122, v123
	v_cvt_pk_bf16_f32 v133, v124, v125
	s_cmp_eq_u64 s[34:35], 0
	s_cbranch_scc1 .Lwt_sb_1
	global_store_dwordx4 v[138:139], v[130:133], off
.Lj_sb_1:
	s_mov_b64 s[40:41], -1
	s_nop 0
	v_cvt_pk_bf16_f32 v130, v94, v95
	v_cvt_pk_bf16_f32 v131, v96, v97
	v_cvt_pk_bf16_f32 v132, v90, v91
	v_cvt_pk_bf16_f32 v133, v92, v93
	s_cmp_eq_u64 s[34:35], 0
	s_cbranch_scc1 .Lwt_sb_2
	global_store_dwordx4 v[138:139], v[130:133], off offset:256
.Lj_sb_2:
	s_nop 1
	v_or_b32_e32 v130, 16, v140
	v_mad_i64_i32 v[130:131], s[0:1], v130, s59, v[134:135]
	v_lshl_add_u64 v[138:139], v[130:131], 0, v[136:137]
	v_cvt_pk_bf16_f32 v130, v118, v119
	v_cvt_pk_bf16_f32 v131, v120, v121
	v_cvt_pk_bf16_f32 v132, v114, v115
	v_cvt_pk_bf16_f32 v133, v116, v117
	s_cmp_eq_u64 s[34:35], 0
	s_cbranch_scc1 .Lwt_sb_3
	global_store_dwordx4 v[138:139], v[130:133], off
.Lj_sb_3:
	s_nop 1
	v_cvt_pk_bf16_f32 v130, v86, v87
	v_cvt_pk_bf16_f32 v131, v88, v89
	v_cvt_pk_bf16_f32 v132, v82, v83
	v_cvt_pk_bf16_f32 v133, v84, v85
	s_cmp_eq_u64 s[34:35], 0
	s_cbranch_scc1 .Lwt_sb_4
	global_store_dwordx4 v[138:139], v[130:133], off offset:256
.Lj_sb_4:
	s_nop 1
	v_or_b32_e32 v130, 32, v140
	v_mad_i64_i32 v[130:131], s[0:1], v130, s59, v[134:135]
	v_lshl_add_u64 v[138:139], v[130:131], 0, v[136:137]
	v_cvt_pk_bf16_f32 v130, v110, v111
	v_cvt_pk_bf16_f32 v131, v112, v113
	v_cvt_pk_bf16_f32 v132, v106, v107
	v_cvt_pk_bf16_f32 v133, v108, v109
	s_cmp_eq_u64 s[34:35], 0
	s_cbranch_scc1 .Lwt_sb_5
	global_store_dwordx4 v[138:139], v[130:133], off
.Lj_sb_5:
	s_nop 1
	v_cvt_pk_bf16_f32 v130, v78, v79
	v_cvt_pk_bf16_f32 v131, v80, v81
	v_cvt_pk_bf16_f32 v132, v74, v75
	v_cvt_pk_bf16_f32 v133, v76, v77
	s_cmp_eq_u64 s[34:35], 0
	s_cbranch_scc1 .Lwt_sb_6
	global_store_dwordx4 v[138:139], v[130:133], off offset:256
.Lj_sb_6:
	s_nop 1
	v_or_b32_e32 v130, 48, v140
	v_mad_i64_i32 v[130:131], s[0:1], v130, s59, v[134:135]
	v_lshl_add_u64 v[138:139], v[130:131], 0, v[136:137]
	v_cvt_pk_bf16_f32 v130, v102, v103
	v_cvt_pk_bf16_f32 v131, v104, v105
	v_cvt_pk_bf16_f32 v132, v98, v99
	v_cvt_pk_bf16_f32 v133, v100, v101
	s_cmp_eq_u64 s[34:35], 0
	s_cbranch_scc1 .Lwt_sb_7
	global_store_dwordx4 v[138:139], v[130:133], off
.Lj_sb_7:
	s_nop 1
	v_cvt_pk_bf16_f32 v130, v70, v71
	v_cvt_pk_bf16_f32 v131, v72, v73
	v_cvt_pk_bf16_f32 v132, v66, v67
	v_cvt_pk_bf16_f32 v133, v68, v69
	s_cmp_eq_u64 s[34:35], 0
	s_cbranch_scc1 .Lwt_sb_8
	global_store_dwordx4 v[138:139], v[130:133], off offset:256
.Lj_sb_8:
	s_nop 1
	v_add_u32_e32 v130, 0x80, v140
	v_mad_i64_i32 v[130:131], s[0:1], v130, s59, v[134:135]
	v_lshl_add_u64 v[138:139], v[130:131], 0, v[136:137]
	v_cvt_pk_bf16_f32 v130, v62, v63
	v_cvt_pk_bf16_f32 v131, v64, v65
	v_cvt_pk_bf16_f32 v132, v58, v59
	v_cvt_pk_bf16_f32 v133, v60, v61
	s_cmp_eq_u64 s[34:35], 0
	s_cbranch_scc1 .Lwt_sb_9
	global_store_dwordx4 v[138:139], v[130:133], off
.Lj_sb_9:
	s_nop 1
	v_cvt_pk_bf16_f32 v130, v30, v31
	v_cvt_pk_bf16_f32 v131, v32, v33
	v_cvt_pk_bf16_f32 v132, v26, v27
	v_cvt_pk_bf16_f32 v133, v28, v29
	s_cmp_eq_u64 s[34:35], 0
	s_cbranch_scc1 .Lwt_sb_10
	global_store_dwordx4 v[138:139], v[130:133], off offset:256
.Lj_sb_10:
	s_nop 1
	v_add_u32_e32 v130, 0x90, v140
	v_mad_i64_i32 v[130:131], s[0:1], v130, s59, v[134:135]
	v_lshl_add_u64 v[138:139], v[130:131], 0, v[136:137]
	v_cvt_pk_bf16_f32 v130, v54, v55
	v_cvt_pk_bf16_f32 v131, v56, v57
	v_cvt_pk_bf16_f32 v132, v50, v51
	v_cvt_pk_bf16_f32 v133, v52, v53
	s_cmp_eq_u64 s[34:35], 0
	s_cbranch_scc1 .Lwt_sb_11
	global_store_dwordx4 v[138:139], v[130:133], off
.Lj_sb_11:
	s_nop 1
	v_cvt_pk_bf16_f32 v130, v22, v23
	v_cvt_pk_bf16_f32 v131, v24, v25
	v_cvt_pk_bf16_f32 v132, v18, v19
	v_cvt_pk_bf16_f32 v133, v20, v21
	s_cmp_eq_u64 s[34:35], 0
	s_cbranch_scc1 .Lwt_sb_12
	global_store_dwordx4 v[138:139], v[130:133], off offset:256
.Lj_sb_12:
	s_nop 1
	v_add_u32_e32 v130, 0xa0, v140
	v_mad_i64_i32 v[130:131], s[0:1], v130, s59, v[134:135]
	v_lshl_add_u64 v[138:139], v[130:131], 0, v[136:137]
	v_cvt_pk_bf16_f32 v130, v46, v47
	v_cvt_pk_bf16_f32 v131, v48, v49
	v_cvt_pk_bf16_f32 v132, v42, v43
	v_cvt_pk_bf16_f32 v133, v44, v45
	s_cmp_eq_u64 s[34:35], 0
	s_cbranch_scc1 .Lwt_sb_13
	global_store_dwordx4 v[138:139], v[130:133], off
.Lj_sb_13:
	s_nop 1
	v_cvt_pk_bf16_f32 v130, v14, v15
	v_cvt_pk_bf16_f32 v131, v16, v17
	v_cvt_pk_bf16_f32 v132, v10, v11
	v_cvt_pk_bf16_f32 v133, v12, v13
	s_cmp_eq_u64 s[34:35], 0
	s_cbranch_scc1 .Lwt_sb_14
	global_store_dwordx4 v[138:139], v[130:133], off offset:256
.Lj_sb_14:
	s_nop 1
	v_add_u32_e32 v130, 0xb0, v140
	v_mad_i64_i32 v[130:131], s[0:1], v130, s59, v[134:135]
	v_lshl_add_u64 v[130:131], v[130:131], 0, v[136:137]
	v_cvt_pk_bf16_f32 v132, v38, v39
	v_cvt_pk_bf16_f32 v133, v40, v41
	v_cvt_pk_bf16_f32 v134, v34, v35
	v_cvt_pk_bf16_f32 v135, v36, v37
	s_cmp_eq_u64 s[34:35], 0
	s_cbranch_scc1 .Lwt_sb_15
	global_store_dwordx4 v[130:131], v[132:135], off
.Lj_sb_15:
.LBB0_901:
	s_and_b64 vcc, exec, s[42:43]
	s_cbranch_vccz .LBB0_907
; __device__ __forceinline__ float bf_lo(unsigned w) { return __uint_as_float(w << 16); }
; __device__ __forceinline__ float bf_hi(unsigned w) { return __uint_as_float(w & 0xffff0000u); }
;     __device__ __forceinline__ bool operator()(f32x4 (&acc)[2][2][4][2], const Unit& u, int wr, int wc, int fr, int fq) const {
;         const int r0 = u.pm * BM + wr * 64 + fr, c0 = u.pn * BM + wc * 32 + fq * 8;
;         const bf16_t* S = u.kh ? SGB : SGR;
; #pragma unroll
;         for (int ai = 0; ai < 2; ++ai)
; #pragma unroll
;             for (int m = 0; m < 4; ++m) { const size_t off = (size_t)(r0 + ai * HALF + m * 16) * D + c0;
; #pragma unroll
;                 for (int bj = 0; bj < 2; ++bj) { const u32x4 s = *(const u32x4*)(S + off + bj * HALF);
;                     f32x4 v0 = acc[ai][bj][m][0], v1 = acc[ai][bj][m][1];
;                     v0[0] *= bf_lo(s.x); v0[1] *= bf_hi(s.x); v0[2] *= bf_lo(s.y); v0[3] *= bf_hi(s.y);
;                     v1[0] *= bf_lo(s.z); v1[1] *= bf_hi(s.z); v1[2] *= bf_lo(s.w); v1[3] *= bf_hi(s.w);
;                     acc[ai][bj][m][0] = v0; acc[ai][bj][m][1] = v1; } }
.LBB0_902:
	s_cmp_eq_u32 s66, 0
	v_lshl_add_u32 v160, s65, 8, v1
	v_lshl_or_b32 v158, s64, 8, v175
	s_cselect_b32 s0, s4, s14
	s_cselect_b32 s1, s5, s15
	v_mov_b32_e32 v130, s0
	v_mov_b32_e32 v131, s1
	v_ashrrev_i32_e32 v159, 31, v158
	v_ashrrev_i32_e32 v161, 31, v160
	v_lshl_add_u64 v[170:171], v[158:159], 1, v[130:131]
	v_lshlrev_b64 v[130:131], 12, v[160:161]
	v_or_b32_e32 v162, 16, v160
	v_lshl_add_u64 v[130:131], v[170:171], 0, v[130:131]
	v_ashrrev_i32_e32 v163, 31, v162
	global_load_dwordx4 v[142:145], v[130:131], off
	global_load_dwordx4 v[178:181], v[130:131], off offset:256
	v_lshlrev_b64 v[130:131], 12, v[162:163]
	v_or_b32_e32 v164, 32, v160
	v_lshl_add_u64 v[130:131], v[170:171], 0, v[130:131]
	v_ashrrev_i32_e32 v165, 31, v164
	global_load_dwordx4 v[182:185], v[130:131], off
	global_load_dwordx4 v[186:189], v[130:131], off offset:256
	v_lshlrev_b64 v[130:131], 12, v[164:165]
	v_lshl_add_u64 v[130:131], v[170:171], 0, v[130:131]
	global_load_dwordx4 v[192:195], v[130:131], off
	global_load_dwordx4 v[196:199], v[130:131], off offset:256
	v_or_b32_e32 v166, 48, v160
	v_add_u32_e32 v168, 0x80, v160
	v_ashrrev_i32_e32 v167, 31, v166
	v_ashrrev_i32_e32 v169, 31, v168
	v_lshlrev_b64 v[130:131], 12, v[166:167]
	v_lshlrev_b64 v[132:133], 12, v[168:169]
	v_lshl_add_u64 v[130:131], v[170:171], 0, v[130:131]
	v_lshl_add_u64 v[134:135], v[170:171], 0, v[132:133]
	global_load_dwordx4 v[200:203], v[130:131], off
	global_load_dwordx4 v[138:141], v[130:131], off offset:256
	s_nop 0
	global_load_dwordx4 v[130:133], v[134:135], off
	s_nop 0
	global_load_dwordx4 v[134:137], v[134:135], off offset:256
	s_cmp_lg_u32 s66, 0
	s_waitcnt vmcnt(0)
	v_lshlrev_b32_e32 v172, 16, v142
	v_and_b32_e32 v173, 0xffff0000, v142
	v_lshlrev_b32_e32 v142, 16, v143
	v_and_b32_e32 v143, 0xffff0000, v143
	v_pk_mul_f32 v[128:129], v[128:129], v[142:143]
	v_lshlrev_b32_e32 v204, 16, v144
	v_and_b32_e32 v205, 0xffff0000, v144
	v_lshlrev_b32_e32 v144, 16, v145
	v_lshlrev_b32_e32 v142, 16, v192
	v_and_b32_e32 v143, 0xffff0000, v192
	v_pk_mul_f32 v[110:111], v[110:111], v[142:143]
	v_lshlrev_b32_e32 v142, 16, v193
	v_and_b32_e32 v143, 0xffff0000, v193
	v_pk_mul_f32 v[112:113], v[112:113], v[142:143]
	v_add_u32_e32 v142, 0x90, v160
	v_and_b32_e32 v145, 0xffff0000, v145
	v_ashrrev_i32_e32 v143, 31, v142
	v_pk_mul_f32 v[124:125], v[124:125], v[144:145]
	v_lshlrev_b64 v[144:145], 12, v[142:143]
	v_lshlrev_b32_e32 v206, 16, v178
	v_and_b32_e32 v207, 0xffff0000, v178
	v_lshlrev_b32_e32 v178, 16, v179
	v_and_b32_e32 v179, 0xffff0000, v179
	v_lshlrev_b32_e32 v208, 16, v180
	v_and_b32_e32 v209, 0xffff0000, v180
	v_lshlrev_b32_e32 v180, 16, v181
	v_and_b32_e32 v181, 0xffff0000, v181
	v_lshl_add_u64 v[144:145], v[170:171], 0, v[144:145]
	v_pk_mul_f32 v[96:97], v[96:97], v[178:179]
	v_pk_mul_f32 v[92:93], v[92:93], v[180:181]
	global_load_dwordx4 v[178:181], v[144:145], off
	v_lshlrev_b32_e32 v210, 16, v182
	v_and_b32_e32 v211, 0xffff0000, v182
	v_lshlrev_b32_e32 v182, 16, v183
	v_and_b32_e32 v183, 0xffff0000, v183
	v_lshlrev_b32_e32 v212, 16, v184
	v_and_b32_e32 v213, 0xffff0000, v184
	v_lshlrev_b32_e32 v184, 16, v185
	v_and_b32_e32 v185, 0xffff0000, v185
	v_pk_mul_f32 v[126:127], v[126:127], v[172:173]
	v_pk_mul_f32 v[120:121], v[120:121], v[182:183]
	v_pk_mul_f32 v[116:117], v[116:117], v[184:185]
	v_lshlrev_b32_e32 v172, 16, v194
	v_and_b32_e32 v173, 0xffff0000, v194
	global_load_dwordx4 v[182:185], v[144:145], off offset:256
	v_lshlrev_b32_e32 v144, 16, v198
	v_and_b32_e32 v145, 0xffff0000, v198
	v_pk_mul_f32 v[106:107], v[106:107], v[172:173]
	v_lshlrev_b32_e32 v172, 16, v195
	v_and_b32_e32 v173, 0xffff0000, v195
	v_pk_mul_f32 v[74:75], v[74:75], v[144:145]
	v_lshlrev_b32_e32 v144, 16, v199
	v_and_b32_e32 v145, 0xffff0000, v199
	v_pk_mul_f32 v[108:109], v[108:109], v[172:173]
	v_lshlrev_b32_e32 v172, 16, v196
	v_and_b32_e32 v173, 0xffff0000, v196
	v_pk_mul_f32 v[76:77], v[76:77], v[144:145]
	v_add_u32_e32 v144, 0xa0, v160
	v_pk_mul_f32 v[78:79], v[78:79], v[172:173]
	v_lshlrev_b32_e32 v172, 16, v197
	v_and_b32_e32 v173, 0xffff0000, v197
	v_ashrrev_i32_e32 v145, 31, v144
	v_pk_mul_f32 v[80:81], v[80:81], v[172:173]
	v_lshlrev_b64 v[172:173], 12, v[144:145]
	v_lshlrev_b32_e32 v214, 16, v186
	v_and_b32_e32 v215, 0xffff0000, v186
	v_lshlrev_b32_e32 v186, 16, v187
	v_and_b32_e32 v187, 0xffff0000, v187
	v_lshlrev_b32_e32 v216, 16, v188
	v_and_b32_e32 v217, 0xffff0000, v188
	v_lshlrev_b32_e32 v188, 16, v189
	v_and_b32_e32 v189, 0xffff0000, v189
	v_lshl_add_u64 v[172:173], v[170:171], 0, v[172:173]
	v_pk_mul_f32 v[88:89], v[88:89], v[186:187]
	v_pk_mul_f32 v[84:85], v[84:85], v[188:189]
	global_load_dwordx4 v[186:189], v[172:173], off
	v_lshlrev_b32_e32 v192, 16, v200
	v_and_b32_e32 v193, 0xffff0000, v200
	v_pk_mul_f32 v[102:103], v[102:103], v[192:193]
	v_lshlrev_b32_e32 v192, 16, v201
	v_and_b32_e32 v193, 0xffff0000, v201
	v_pk_mul_f32 v[104:105], v[104:105], v[192:193]
	v_lshlrev_b32_e32 v192, 16, v202
	v_and_b32_e32 v193, 0xffff0000, v202
	v_pk_mul_f32 v[98:99], v[98:99], v[192:193]
	global_load_dwordx4 v[192:195], v[172:173], off offset:256
	v_lshlrev_b32_e32 v172, 16, v138
	v_and_b32_e32 v173, 0xffff0000, v138
	v_pk_mul_f32 v[70:71], v[70:71], v[172:173]
	v_add_u32_e32 v172, 0xb0, v160
	v_lshlrev_b32_e32 v138, 16, v139
	v_and_b32_e32 v139, 0xffff0000, v139
	v_ashrrev_i32_e32 v173, 31, v172
	v_pk_mul_f32 v[72:73], v[72:73], v[138:139]
	v_lshlrev_b64 v[138:139], 12, v[172:173]
	v_lshlrev_b32_e32 v196, 16, v203
	v_and_b32_e32 v197, 0xffff0000, v203
	v_lshl_add_u64 v[138:139], v[170:171], 0, v[138:139]
	v_pk_mul_f32 v[100:101], v[100:101], v[196:197]
	global_load_dwordx4 v[196:199], v[138:139], off
	v_lshlrev_b32_e32 v170, 16, v140
	v_and_b32_e32 v171, 0xffff0000, v140
	v_lshlrev_b32_e32 v140, 16, v141
	v_and_b32_e32 v141, 0xffff0000, v141
	v_pk_mul_f32 v[68:69], v[68:69], v[140:141]
	v_lshlrev_b32_e32 v140, 16, v130
	v_and_b32_e32 v141, 0xffff0000, v130
	v_pk_mul_f32 v[62:63], v[62:63], v[140:141]
	global_load_dwordx4 v[138:141], v[138:139], off offset:256
	v_lshlrev_b32_e32 v130, 16, v131
	v_and_b32_e32 v131, 0xffff0000, v131
	v_pk_mul_f32 v[64:65], v[64:65], v[130:131]
	v_lshlrev_b32_e32 v130, 16, v132
	v_and_b32_e32 v131, 0xffff0000, v132
	v_pk_mul_f32 v[58:59], v[58:59], v[130:131]
	v_lshlrev_b32_e32 v130, 16, v133
	v_and_b32_e32 v131, 0xffff0000, v133
	v_pk_mul_f32 v[60:61], v[60:61], v[130:131]
	v_lshlrev_b32_e32 v130, 16, v134
	v_and_b32_e32 v131, 0xffff0000, v134
	v_pk_mul_f32 v[30:31], v[30:31], v[130:131]
	v_lshlrev_b32_e32 v130, 16, v135
	v_and_b32_e32 v131, 0xffff0000, v135
	v_pk_mul_f32 v[32:33], v[32:33], v[130:131]
	v_lshlrev_b32_e32 v130, 16, v136
	v_and_b32_e32 v131, 0xffff0000, v136
	v_pk_mul_f32 v[26:27], v[26:27], v[130:131]
	v_lshlrev_b32_e32 v130, 16, v137
	v_and_b32_e32 v131, 0xffff0000, v137
	v_pk_mul_f32 v[28:29], v[28:29], v[130:131]
	s_waitcnt vmcnt(0)
; __device__ __forceinline__ unsigned pk_bf16(float lo, float hi) { const f32x2_t v = {lo, hi}; return __builtin_bit_cast(unsigned, __builtin_convertvector(v, bf16x2_t)); }
; __device__ __forceinline__ float bf_lo(unsigned w) { return __uint_as_float(w << 16); }
; __device__ __forceinline__ float bf_hi(unsigned w) { return __uint_as_float(w & 0xffff0000u); }
;     __device__ __forceinline__ bool operator()(f32x4 (&acc)[2][2][4][2], const Unit& u, int wr, int wc, int fr, int fq) const {
;     ...
;                 for (int bj = 0; bj < 2; ++bj) { const u32x4 s = *(const u32x4*)(S + off + bj * HALF);
;                     f32x4 v0 = acc[ai][bj][m][0], v1 = acc[ai][bj][m][1];
;                     v0[0] *= bf_lo(s.x); v0[1] *= bf_hi(s.x); v0[2] *= bf_lo(s.y); v0[3] *= bf_hi(s.y);
;                     v1[0] *= bf_lo(s.z); v1[1] *= bf_hi(s.z); v1[2] *= bf_lo(s.w); v1[3] *= bf_hi(s.w);
;                     acc[ai][bj][m][0] = v0; acc[ai][bj][m][1] = v1; } }
;         if (u.kh == 0) return false;
; #pragma unroll
;         for (int ai = 0; ai < 2; ++ai)
; #pragma unroll
;             for (int m = 0; m < 4; ++m) { const size_t off = (size_t)(r0 + ai * HALF + m * 16) * LDP + c0;
; #pragma unroll
;                 for (int bj = 0; bj < 2; ++bj) { const f32x4 v0 = acc[ai][bj][m][0], v1 = acc[ai][bj][m][1];
;                     u32x4 w; w.x = pk_bf16(v0[0], v0[1]); w.y = pk_bf16(v0[2], v0[3]); w.z = pk_bf16(v1[0], v1[1]); w.w = pk_bf16(v1[2], v1[3]);
;                     *(u32x4*)(MG + off + bj * HALF) = w; } }
	v_lshlrev_b32_e32 v130, 16, v178
	v_and_b32_e32 v131, 0xffff0000, v178
	v_pk_mul_f32 v[54:55], v[54:55], v[130:131]
	v_lshlrev_b32_e32 v130, 16, v179
	v_and_b32_e32 v131, 0xffff0000, v179
	v_pk_mul_f32 v[56:57], v[56:57], v[130:131]
	v_lshlrev_b32_e32 v130, 16, v180
	v_and_b32_e32 v131, 0xffff0000, v180
	v_pk_mul_f32 v[50:51], v[50:51], v[130:131]
	v_lshlrev_b32_e32 v130, 16, v181
	v_and_b32_e32 v131, 0xffff0000, v181
	v_pk_mul_f32 v[52:53], v[52:53], v[130:131]
	v_lshlrev_b32_e32 v130, 16, v182
	v_and_b32_e32 v131, 0xffff0000, v182
	v_pk_mul_f32 v[22:23], v[22:23], v[130:131]
	v_lshlrev_b32_e32 v130, 16, v183
	v_and_b32_e32 v131, 0xffff0000, v183
	v_pk_mul_f32 v[24:25], v[24:25], v[130:131]
	v_lshlrev_b32_e32 v130, 16, v184
	v_and_b32_e32 v131, 0xffff0000, v184
	v_pk_mul_f32 v[18:19], v[18:19], v[130:131]
	v_lshlrev_b32_e32 v130, 16, v185
	v_and_b32_e32 v131, 0xffff0000, v185
	v_pk_mul_f32 v[20:21], v[20:21], v[130:131]
	v_pk_mul_f32 v[122:123], v[122:123], v[204:205]
	v_lshlrev_b32_e32 v130, 16, v186
	v_and_b32_e32 v131, 0xffff0000, v186
	v_pk_mul_f32 v[46:47], v[46:47], v[130:131]
	v_lshlrev_b32_e32 v130, 16, v187
	v_and_b32_e32 v131, 0xffff0000, v187
	v_pk_mul_f32 v[48:49], v[48:49], v[130:131]
	v_lshlrev_b32_e32 v130, 16, v188
	v_and_b32_e32 v131, 0xffff0000, v188
	v_pk_mul_f32 v[42:43], v[42:43], v[130:131]
	v_lshlrev_b32_e32 v130, 16, v189
	v_and_b32_e32 v131, 0xffff0000, v189
	v_pk_mul_f32 v[44:45], v[44:45], v[130:131]
	v_lshlrev_b32_e32 v130, 16, v192
	v_and_b32_e32 v131, 0xffff0000, v192
	v_pk_mul_f32 v[14:15], v[14:15], v[130:131]
	v_lshlrev_b32_e32 v130, 16, v193
	v_and_b32_e32 v131, 0xffff0000, v193
	v_pk_mul_f32 v[16:17], v[16:17], v[130:131]
	v_lshlrev_b32_e32 v130, 16, v194
	v_and_b32_e32 v131, 0xffff0000, v194
	v_pk_mul_f32 v[10:11], v[10:11], v[130:131]
	v_lshlrev_b32_e32 v130, 16, v195
	v_and_b32_e32 v131, 0xffff0000, v195
	v_pk_mul_f32 v[12:13], v[12:13], v[130:131]
	v_lshlrev_b32_e32 v130, 16, v196
	v_and_b32_e32 v131, 0xffff0000, v196
	v_pk_mul_f32 v[38:39], v[38:39], v[130:131]
	v_lshlrev_b32_e32 v130, 16, v197
	v_and_b32_e32 v131, 0xffff0000, v197
	v_pk_mul_f32 v[40:41], v[40:41], v[130:131]
	v_lshlrev_b32_e32 v130, 16, v198
	v_and_b32_e32 v131, 0xffff0000, v198
	v_pk_mul_f32 v[34:35], v[34:35], v[130:131]
	v_lshlrev_b32_e32 v130, 16, v199
	v_and_b32_e32 v131, 0xffff0000, v199
	v_pk_mul_f32 v[36:37], v[36:37], v[130:131]
	v_lshlrev_b32_e32 v130, 16, v138
	v_and_b32_e32 v131, 0xffff0000, v138
	v_pk_mul_f32 v[6:7], v[6:7], v[130:131]
	v_lshlrev_b32_e32 v130, 16, v140
	v_and_b32_e32 v131, 0xffff0000, v140
	v_pk_mul_f32 v[94:95], v[94:95], v[206:207]
	v_pk_mul_f32 v[90:91], v[90:91], v[208:209]
	v_pk_mul_f32 v[118:119], v[118:119], v[210:211]
	v_pk_mul_f32 v[114:115], v[114:115], v[212:213]
	v_pk_mul_f32 v[86:87], v[86:87], v[214:215]
	v_pk_mul_f32 v[82:83], v[82:83], v[216:217]
	v_pk_mul_f32 v[66:67], v[66:67], v[170:171]
	v_pk_mul_f32 v[2:3], v[2:3], v[130:131]
	s_cbranch_scc0 .LBB0_904
	v_mov_b64_e32 v[136:137], s[12:13]
	v_mad_i64_i32 v[134:135], s[0:1], v160, s59, v[136:137]
	v_lshlrev_b64 v[158:159], 1, v[158:159]
	v_cvt_pk_bf16_f32 v130, v126, v127
	v_cvt_pk_bf16_f32 v131, v128, v129
	v_cvt_pk_bf16_f32 v132, v122, v123
	v_cvt_pk_bf16_f32 v133, v124, v125
	v_lshl_add_u64 v[134:135], v[134:135], 0, v[158:159]
	s_cmp_eq_u64 s[34:35], 0
	s_cbranch_scc1 .Lwt_sb_16
	global_store_dwordx4 v[134:135], v[130:133], off
.Lj_sb_16:
	s_mov_b64 s[40:41], -1
	s_nop 0
	v_cvt_pk_bf16_f32 v130, v94, v95
	v_cvt_pk_bf16_f32 v131, v96, v97
	v_cvt_pk_bf16_f32 v132, v90, v91
	v_cvt_pk_bf16_f32 v133, v92, v93
	s_cmp_eq_u64 s[34:35], 0
	s_cbranch_scc1 .Lwt_sb_17
	global_store_dwordx4 v[134:135], v[130:133], off offset:256
.Lj_sb_17:
	v_mad_i64_i32 v[134:135], s[0:1], v162, s59, v[136:137]
	s_nop 0
	v_cvt_pk_bf16_f32 v130, v118, v119
	v_cvt_pk_bf16_f32 v131, v120, v121
	v_cvt_pk_bf16_f32 v132, v114, v115
	v_cvt_pk_bf16_f32 v133, v116, v117
	v_lshl_add_u64 v[134:135], v[134:135], 0, v[158:159]
	s_cmp_eq_u64 s[34:35], 0
	s_cbranch_scc1 .Lwt_sb_18
	global_store_dwordx4 v[134:135], v[130:133], off
; __device__ __forceinline__ unsigned pk_bf16(float lo, float hi) { const f32x2_t v = {lo, hi}; return __builtin_bit_cast(unsigned, __builtin_convertvector(v, bf16x2_t)); }
;     __device__ __forceinline__ bool operator()(f32x4 (&acc)[2][2][4][2], const Unit& u, int wr, int wc, int fr, int fq) const {
;     ...
;             for (int m = 0; m < 4; ++m) { const size_t off = (size_t)(r0 + ai * HALF + m * 16) * LDP + c0;
; #pragma unroll
;                 for (int bj = 0; bj < 2; ++bj) { const f32x4 v0 = acc[ai][bj][m][0], v1 = acc[ai][bj][m][1];
;                     u32x4 w; w.x = pk_bf16(v0[0], v0[1]); w.y = pk_bf16(v0[2], v0[3]); w.z = pk_bf16(v1[0], v1[1]); w.w = pk_bf16(v1[2], v1[3]);
;                     *(u32x4*)(MG + off + bj * HALF) = w; } }
.Lj_sb_18:
	s_nop 1
	v_cvt_pk_bf16_f32 v130, v86, v87
	v_cvt_pk_bf16_f32 v131, v88, v89
	v_cvt_pk_bf16_f32 v132, v82, v83
	v_cvt_pk_bf16_f32 v133, v84, v85
	s_cmp_eq_u64 s[34:35], 0
	s_cbranch_scc1 .Lwt_sb_19
	global_store_dwordx4 v[134:135], v[130:133], off offset:256
.Lj_sb_19:
	v_mad_i64_i32 v[134:135], s[0:1], v164, s59, v[136:137]
	s_nop 0
	v_cvt_pk_bf16_f32 v130, v110, v111
	v_cvt_pk_bf16_f32 v131, v112, v113
	v_cvt_pk_bf16_f32 v132, v106, v107
	v_cvt_pk_bf16_f32 v133, v108, v109
	v_lshl_add_u64 v[134:135], v[134:135], 0, v[158:159]
	s_cmp_eq_u64 s[34:35], 0
	s_cbranch_scc1 .Lwt_sb_20
	global_store_dwordx4 v[134:135], v[130:133], off
.Lj_sb_20:
	s_nop 1
	v_cvt_pk_bf16_f32 v130, v78, v79
	v_cvt_pk_bf16_f32 v131, v80, v81
	v_cvt_pk_bf16_f32 v132, v74, v75
	v_cvt_pk_bf16_f32 v133, v76, v77
	s_cmp_eq_u64 s[34:35], 0
	s_cbranch_scc1 .Lwt_sb_21
	global_store_dwordx4 v[134:135], v[130:133], off offset:256
.Lj_sb_21:
	v_mad_i64_i32 v[134:135], s[0:1], v166, s59, v[136:137]
	s_nop 0
	v_cvt_pk_bf16_f32 v130, v102, v103
	v_cvt_pk_bf16_f32 v131, v104, v105
	v_cvt_pk_bf16_f32 v132, v98, v99
	v_cvt_pk_bf16_f32 v133, v100, v101
	v_lshl_add_u64 v[134:135], v[134:135], 0, v[158:159]
	s_cmp_eq_u64 s[34:35], 0
	s_cbranch_scc1 .Lwt_sb_22
	global_store_dwordx4 v[134:135], v[130:133], off
.Lj_sb_22:
	s_nop 1
	v_cvt_pk_bf16_f32 v130, v70, v71
	v_cvt_pk_bf16_f32 v131, v72, v73
	v_cvt_pk_bf16_f32 v132, v66, v67
	v_cvt_pk_bf16_f32 v133, v68, v69
	s_cmp_eq_u64 s[34:35], 0
	s_cbranch_scc1 .Lwt_sb_23
	global_store_dwordx4 v[134:135], v[130:133], off offset:256
.Lj_sb_23:
	v_mad_i64_i32 v[134:135], s[0:1], v168, s59, v[136:137]
	s_nop 0
	v_cvt_pk_bf16_f32 v130, v62, v63
	v_cvt_pk_bf16_f32 v131, v64, v65
	v_cvt_pk_bf16_f32 v132, v58, v59
	v_cvt_pk_bf16_f32 v133, v60, v61
	v_lshl_add_u64 v[134:135], v[134:135], 0, v[158:159]
	s_cmp_eq_u64 s[34:35], 0
	s_cbranch_scc1 .Lwt_sb_24
	global_store_dwordx4 v[134:135], v[130:133], off
.Lj_sb_24:
	s_nop 1
	v_cvt_pk_bf16_f32 v130, v30, v31
	v_cvt_pk_bf16_f32 v131, v32, v33
	v_cvt_pk_bf16_f32 v132, v26, v27
	v_cvt_pk_bf16_f32 v133, v28, v29
	s_cmp_eq_u64 s[34:35], 0
	s_cbranch_scc1 .Lwt_sb_25
	global_store_dwordx4 v[134:135], v[130:133], off offset:256
.Lj_sb_25:
	v_mad_i64_i32 v[134:135], s[0:1], v142, s59, v[136:137]
	s_nop 0
	v_cvt_pk_bf16_f32 v130, v54, v55
	v_cvt_pk_bf16_f32 v131, v56, v57
	v_cvt_pk_bf16_f32 v132, v50, v51
	v_cvt_pk_bf16_f32 v133, v52, v53
	v_lshl_add_u64 v[134:135], v[134:135], 0, v[158:159]
	s_cmp_eq_u64 s[34:35], 0
	s_cbranch_scc1 .Lwt_sb_26
	global_store_dwordx4 v[134:135], v[130:133], off
.Lj_sb_26:
	s_nop 1
	v_cvt_pk_bf16_f32 v130, v22, v23
	v_cvt_pk_bf16_f32 v131, v24, v25
	v_cvt_pk_bf16_f32 v132, v18, v19
	v_cvt_pk_bf16_f32 v133, v20, v21
	s_cmp_eq_u64 s[34:35], 0
	s_cbranch_scc1 .Lwt_sb_27
	global_store_dwordx4 v[134:135], v[130:133], off offset:256
.Lj_sb_27:
	v_mad_i64_i32 v[134:135], s[0:1], v144, s59, v[136:137]
	s_nop 0
	v_cvt_pk_bf16_f32 v130, v46, v47
	v_cvt_pk_bf16_f32 v131, v48, v49
	v_cvt_pk_bf16_f32 v132, v42, v43
	v_cvt_pk_bf16_f32 v133, v44, v45
	v_lshl_add_u64 v[134:135], v[134:135], 0, v[158:159]
	s_cmp_eq_u64 s[34:35], 0
	s_cbranch_scc1 .Lwt_sb_28
	global_store_dwordx4 v[134:135], v[130:133], off
.Lj_sb_28:
	s_nop 1
	v_cvt_pk_bf16_f32 v130, v14, v15
	v_cvt_pk_bf16_f32 v131, v16, v17
	v_cvt_pk_bf16_f32 v132, v10, v11
	v_cvt_pk_bf16_f32 v133, v12, v13
	s_cmp_eq_u64 s[34:35], 0
	s_cbranch_scc1 .Lwt_sb_29
	global_store_dwordx4 v[134:135], v[130:133], off offset:256
.Lj_sb_29:
	v_cvt_pk_bf16_f32 v134, v34, v35
	v_cvt_pk_bf16_f32 v135, v36, v37
	v_mad_i64_i32 v[130:131], s[0:1], v172, s59, v[136:137]
	v_cvt_pk_bf16_f32 v132, v38, v39
	v_cvt_pk_bf16_f32 v133, v40, v41
	v_lshl_add_u64 v[130:131], v[130:131], 0, v[158:159]
	s_cmp_eq_u64 s[34:35], 0
	s_cbranch_scc1 .Lwt_sb_30
	global_store_dwordx4 v[130:131], v[132:135], off
.Lj_sb_30:
.LBB0_904:
	s_nop 1
	v_lshlrev_b32_e32 v132, 16, v139
	v_and_b32_e32 v133, 0xffff0000, v139
	v_pk_mul_f32 v[8:9], v[8:9], v[132:133]
	v_lshlrev_b32_e32 v132, 16, v141
	v_and_b32_e32 v133, 0xffff0000, v141
	v_pk_mul_f32 v[4:5], v[4:5], v[132:133]
	s_mov_b64 s[42:43], 0
	s_and_b64 vcc, exec, s[40:41]
	s_cbranch_vccnz .LBB0_908

; __device__ __forceinline__ unsigned pk_bf16(float lo, float hi) { const f32x2_t v = {lo, hi}; return __builtin_bit_cast(unsigned, __builtin_convertvector(v, bf16x2_t)); }
; template <int MODE  , class Epi, class Sched>
; __device__ __forceinline__ void gemm_phase(LAS unsigned char* lds, const GemmDesc g, const Sched& S, const Epi& E) {
;     ...
;         if (zero) {
; #pragma unroll
;             for (int a = 0; a < 2; ++a)
; #pragma unroll
;                 for (int b = 0; b < 2; ++b)
; #pragma unroll
;                     for (int m = 0; m < 4; ++m)
; #pragma unroll
;                         for (int n = 0; n < 2; ++n) acc[a][b][m][n] = (f32x4){0.f, 0.f, 0.f, 0.f};
;         }
;     __device__ __forceinline__ bool operator()(f32x4 (&acc)[2][2][4][2], const Unit& u, int wr, int wc, int fr, int fq) const {
;     ...
;                 for (int bj = 0; bj < 2; ++bj) { const f32x4 v0 = acc[ai][bj][m][0], v1 = acc[ai][bj][m][1];
;                     u32x4 w; w.x = pk_bf16(v0[0], v0[1]); w.y = pk_bf16(v0[2], v0[3]); w.z = pk_bf16(v1[0], v1[1]); w.w = pk_bf16(v1[2], v1[3]);
;                     *(u32x4*)(MG + off + bj * HALF) = w; } }
;         return true;
.LBB0_908:
	v_cvt_pk_bf16_f32 v132, v6, v7
	v_cvt_pk_bf16_f32 v133, v8, v9
	v_cvt_pk_bf16_f32 v134, v2, v3
	v_cvt_pk_bf16_f32 v135, v4, v5
	s_mov_b64 s[42:43], -1
	s_cmp_eq_u64 s[34:35], 0
	s_cbranch_scc1 .Lwt_sb_31
	global_store_dwordx4 v[130:131], v[132:135], off offset:256
.Lj_sb_31:
	s_mov_b64 s[40:41], -1
	s_and_b64 vcc, exec, s[34:35]
	s_cbranch_vccz .LBB0_885
.LBB0_909:
	s_andn2_b64 vcc, exec, s[42:43]
	s_cbranch_vccnz .LBB0_884
	v_mov_b32_e32 v2, 0
	v_mov_b32_e32 v3, v2
	v_mov_b64_e32 v[4:5], v[2:3]
	v_mov_b64_e32 v[6:7], v[2:3]
	v_mov_b64_e32 v[8:9], v[2:3]
	v_mov_b64_e32 v[10:11], v[2:3]
	v_mov_b64_e32 v[12:13], v[2:3]
	v_mov_b64_e32 v[14:15], v[2:3]
	v_mov_b64_e32 v[16:17], v[2:3]
	v_mov_b64_e32 v[18:19], v[2:3]
	v_mov_b64_e32 v[20:21], v[2:3]
	v_mov_b64_e32 v[22:23], v[2:3]
	v_mov_b64_e32 v[24:25], v[2:3]
	v_mov_b64_e32 v[26:27], v[2:3]
	v_mov_b64_e32 v[28:29], v[2:3]
	v_mov_b64_e32 v[30:31], v[2:3]
	v_mov_b64_e32 v[32:33], v[2:3]
	v_mov_b64_e32 v[34:35], v[2:3]
	v_mov_b64_e32 v[36:37], v[2:3]
	v_mov_b64_e32 v[38:39], v[2:3]
	v_mov_b64_e32 v[40:41], v[2:3]
	v_mov_b64_e32 v[42:43], v[2:3]
	v_mov_b64_e32 v[44:45], v[2:3]
	v_mov_b64_e32 v[46:47], v[2:3]
	v_mov_b64_e32 v[48:49], v[2:3]
	v_mov_b64_e32 v[50:51], v[2:3]
	v_mov_b64_e32 v[52:53], v[2:3]
	v_mov_b64_e32 v[54:55], v[2:3]
	v_mov_b64_e32 v[56:57], v[2:3]
	v_mov_b64_e32 v[58:59], v[2:3]
	v_mov_b64_e32 v[60:61], v[2:3]
	v_mov_b64_e32 v[62:63], v[2:3]
	v_mov_b64_e32 v[64:65], v[2:3]
	v_mov_b64_e32 v[66:67], v[2:3]
	v_mov_b64_e32 v[68:69], v[2:3]
	v_mov_b64_e32 v[70:71], v[2:3]
	v_mov_b64_e32 v[72:73], v[2:3]
	v_mov_b64_e32 v[74:75], v[2:3]
	v_mov_b64_e32 v[76:77], v[2:3]
	v_mov_b64_e32 v[78:79], v[2:3]
	v_mov_b64_e32 v[80:81], v[2:3]
	v_mov_b64_e32 v[82:83], v[2:3]
	v_mov_b64_e32 v[84:85], v[2:3]
	v_mov_b64_e32 v[86:87], v[2:3]
	v_mov_b64_e32 v[88:89], v[2:3]
	v_mov_b64_e32 v[90:91], v[2:3]
	v_mov_b64_e32 v[92:93], v[2:3]
	v_mov_b64_e32 v[94:95], v[2:3]
	v_mov_b64_e32 v[96:97], v[2:3]
	v_mov_b64_e32 v[98:99], v[2:3]
	v_mov_b64_e32 v[100:101], v[2:3]
	v_mov_b64_e32 v[102:103], v[2:3]
	v_mov_b64_e32 v[104:105], v[2:3]
	v_mov_b64_e32 v[106:107], v[2:3]
	v_mov_b64_e32 v[108:109], v[2:3]
	v_mov_b64_e32 v[110:111], v[2:3]
	v_mov_b64_e32 v[112:113], v[2:3]
	v_mov_b64_e32 v[114:115], v[2:3]
	v_mov_b64_e32 v[116:117], v[2:3]
	v_mov_b64_e32 v[118:119], v[2:3]
	v_mov_b64_e32 v[120:121], v[2:3]
	v_mov_b64_e32 v[122:123], v[2:3]
	v_mov_b64_e32 v[124:125], v[2:3]
	v_mov_b64_e32 v[126:127], v[2:3]
	v_mov_b64_e32 v[128:129], v[2:3]
	s_branch .LBB0_884

; __device__ __forceinline__ unsigned pk_bf16(float lo, float hi) { const f32x2_t v = {lo, hi}; return __builtin_bit_cast(unsigned, __builtin_convertvector(v, bf16x2_t)); }
;     __device__ __forceinline__ bool operator()(f32x4 (&acc)[2][2][4][2], const Unit& u, int wr, int wc, int fr, int fq) const {
;     ...
;             for (int m = 0; m < 4; ++m) { bf16_t* rowp = DL + (size_t)(r0 + ai * HALF + m * 16) * LDP + c0;
; #pragma unroll
;                 for (int bj = 0; bj < 2; ++bj) { const f32x4 v0 = acc[ai][bj][m][0], v1 = acc[ai][bj][m][1];
;                     u32x4 w; w.x = pk_bf16(v0[0], v0[1]); w.y = pk_bf16(v0[2], v0[3]); w.z = pk_bf16(v1[0], v1[1]); w.w = pk_bf16(v1[2], v1[3]);
;                     *(u32x4*)(rowp + bj * HALF) = w; } }
.Lwt_sc_1:
	global_store_dwordx4 v[154:155], v[146:149], off sc1
	s_branch .Lj_sc_1
.Lwt_sc_2:
	global_store_dwordx4 v[154:155], v[146:149], off offset:256 sc1
	s_branch .Lj_sc_2

; __device__ __forceinline__ unsigned pk_bf16(float lo, float hi) { const f32x2_t v = {lo, hi}; return __builtin_bit_cast(unsigned, __builtin_convertvector(v, bf16x2_t)); }
;     __device__ __forceinline__ bool operator()(f32x4 (&acc)[2][2][4][2], const Unit& u, int wr, int wc, int fr, int fq) const {
;     ...
;             for (int m = 0; m < 4; ++m) { bf16_t* rowp = DL + (size_t)(r0 + ai * HALF + m * 16) * LDP + c0;
; #pragma unroll
;                 for (int bj = 0; bj < 2; ++bj) { const f32x4 v0 = acc[ai][bj][m][0], v1 = acc[ai][bj][m][1];
;                     u32x4 w; w.x = pk_bf16(v0[0], v0[1]); w.y = pk_bf16(v0[2], v0[3]); w.z = pk_bf16(v1[0], v1[1]); w.w = pk_bf16(v1[2], v1[3]);
;                     *(u32x4*)(rowp + bj * HALF) = w; } }
.Lwt_sc_15:
	global_store_dwordx4 v[150:151], v[146:149], off sc1
	s_branch .Lj_sc_15
.Lwt_sc_16:
	global_store_dwordx4 v[150:151], v[146:149], off offset:256 sc1
	s_branch .Lj_sc_16

; __device__ __forceinline__ unsigned pk_bf16(float lo, float hi) { const f32x2_t v = {lo, hi}; return __builtin_bit_cast(unsigned, __builtin_convertvector(v, bf16x2_t)); }
;     __device__ __forceinline__ bool operator()(f32x4 (&acc)[2][2][4][2], const Unit& u, int wr, int wc, int fr, int fq) const {
;         const int r0 = u.pm * BM + wr * 64 + fr, c0 = u.pn * BM + wc * 32 + fq * 8;
; #pragma unroll
;         for (int ai = 0; ai < 2; ++ai)
; #pragma unroll
;             for (int m = 0; m < 4; ++m) { bf16_t* rowp = DL + (size_t)(r0 + ai * HALF + m * 16) * LDP + c0;
; #pragma unroll
;                 for (int bj = 0; bj < 2; ++bj) { const f32x4 v0 = acc[ai][bj][m][0], v1 = acc[ai][bj][m][1];
;                     u32x4 w; w.x = pk_bf16(v0[0], v0[1]); w.y = pk_bf16(v0[2], v0[3]); w.z = pk_bf16(v1[0], v1[1]); w.w = pk_bf16(v1[2], v1[3]);
;                     *(u32x4*)(rowp + bj * HALF) = w; } }
;     __device__ __forceinline__ bool operator()(f32x4 (&acc)[2][2][4][2], const Unit& u, int wr, int wc, int fr, int fq) const {
;     ...
;         if (u.kh == 0) return false;
;         return e(acc, u, wr, wc, fr, fq);
.Lkepi_sc:
	s_cmp_lg_u32 s57, 0
	s_cselect_b64 s[34:35], -1, 0
	s_cmp_eq_u32 s57, 0
	s_cbranch_scc1 .LBB0_990
	v_lshl_or_b32 v146, s58, 8, v143
	v_lshl_add_u32 v145, s56, 8, v1
	v_ashrrev_i32_e32 v147, 31, v146
	v_mov_b64_e32 v[150:151], s[26:27]
	v_mad_i64_i32 v[148:149], s[0:1], v145, s52, v[150:151]
	v_lshlrev_b64 v[152:153], 1, v[146:147]
	v_lshl_add_u64 v[154:155], v[148:149], 0, v[152:153]
	v_cvt_pk_bf16_f32 v146, v126, v127
	v_cvt_pk_bf16_f32 v147, v128, v129
	v_cvt_pk_bf16_f32 v148, v122, v123
	v_cvt_pk_bf16_f32 v149, v124, v125
	s_cmp_eq_u64 s[18:19], 0
	s_cbranch_scc1 .Lwt_sc_1
	global_store_dwordx4 v[154:155], v[146:149], off
.Lj_sc_1:
	s_nop 1
	v_cvt_pk_bf16_f32 v146, v94, v95
	v_cvt_pk_bf16_f32 v147, v96, v97
	v_cvt_pk_bf16_f32 v148, v90, v91
	v_cvt_pk_bf16_f32 v149, v92, v93
	s_cmp_eq_u64 s[18:19], 0
	s_cbranch_scc1 .Lwt_sc_2
	global_store_dwordx4 v[154:155], v[146:149], off offset:256
.Lj_sc_2:
	s_nop 1
	v_or_b32_e32 v146, 16, v145
	v_mad_i64_i32 v[146:147], s[0:1], v146, s52, v[150:151]
	v_lshl_add_u64 v[154:155], v[146:147], 0, v[152:153]
	v_cvt_pk_bf16_f32 v146, v118, v119
	v_cvt_pk_bf16_f32 v147, v120, v121
	v_cvt_pk_bf16_f32 v148, v114, v115
	v_cvt_pk_bf16_f32 v149, v116, v117
	s_cmp_eq_u64 s[18:19], 0
	s_cbranch_scc1 .Lwt_sc_3
	global_store_dwordx4 v[154:155], v[146:149], off
.Lj_sc_3:
	s_nop 1
	v_cvt_pk_bf16_f32 v146, v86, v87
	v_cvt_pk_bf16_f32 v147, v88, v89
	v_cvt_pk_bf16_f32 v148, v82, v83
	v_cvt_pk_bf16_f32 v149, v84, v85
	s_cmp_eq_u64 s[18:19], 0
	s_cbranch_scc1 .Lwt_sc_4
	global_store_dwordx4 v[154:155], v[146:149], off offset:256
.Lj_sc_4:
	s_nop 1
	v_or_b32_e32 v146, 32, v145
	v_mad_i64_i32 v[146:147], s[0:1], v146, s52, v[150:151]
	v_lshl_add_u64 v[154:155], v[146:147], 0, v[152:153]
	v_cvt_pk_bf16_f32 v146, v110, v111
	v_cvt_pk_bf16_f32 v147, v112, v113
	v_cvt_pk_bf16_f32 v148, v106, v107
	v_cvt_pk_bf16_f32 v149, v108, v109
	s_cmp_eq_u64 s[18:19], 0
	s_cbranch_scc1 .Lwt_sc_5
	global_store_dwordx4 v[154:155], v[146:149], off
.Lj_sc_5:
	s_nop 1
	v_cvt_pk_bf16_f32 v146, v78, v79
	v_cvt_pk_bf16_f32 v147, v80, v81
	v_cvt_pk_bf16_f32 v148, v74, v75
	v_cvt_pk_bf16_f32 v149, v76, v77
	s_cmp_eq_u64 s[18:19], 0
	s_cbranch_scc1 .Lwt_sc_6
	global_store_dwordx4 v[154:155], v[146:149], off offset:256
.Lj_sc_6:
	s_nop 1
	v_or_b32_e32 v146, 48, v145
	v_mad_i64_i32 v[146:147], s[0:1], v146, s52, v[150:151]
	v_lshl_add_u64 v[154:155], v[146:147], 0, v[152:153]
	v_cvt_pk_bf16_f32 v146, v102, v103
	v_cvt_pk_bf16_f32 v147, v104, v105
	v_cvt_pk_bf16_f32 v148, v98, v99
	v_cvt_pk_bf16_f32 v149, v100, v101
	s_cmp_eq_u64 s[18:19], 0
	s_cbranch_scc1 .Lwt_sc_7
	global_store_dwordx4 v[154:155], v[146:149], off
.Lj_sc_7:
	s_nop 1
	v_cvt_pk_bf16_f32 v146, v70, v71
	v_cvt_pk_bf16_f32 v147, v72, v73
	v_cvt_pk_bf16_f32 v148, v66, v67
	v_cvt_pk_bf16_f32 v149, v68, v69
	s_cmp_eq_u64 s[18:19], 0
	s_cbranch_scc1 .Lwt_sc_8
	global_store_dwordx4 v[154:155], v[146:149], off offset:256
.Lj_sc_8:
	s_nop 1
	v_add_u32_e32 v146, 0x80, v145
	v_mad_i64_i32 v[146:147], s[0:1], v146, s52, v[150:151]
	v_lshl_add_u64 v[154:155], v[146:147], 0, v[152:153]
	v_cvt_pk_bf16_f32 v146, v62, v63
	v_cvt_pk_bf16_f32 v147, v64, v65
	v_cvt_pk_bf16_f32 v148, v58, v59
	v_cvt_pk_bf16_f32 v149, v60, v61
	s_cmp_eq_u64 s[18:19], 0
	s_cbranch_scc1 .Lwt_sc_9
	global_store_dwordx4 v[154:155], v[146:149], off
.Lj_sc_9:
	s_nop 1
	v_cvt_pk_bf16_f32 v146, v30, v31
	v_cvt_pk_bf16_f32 v147, v32, v33
	v_cvt_pk_bf16_f32 v148, v26, v27
	v_cvt_pk_bf16_f32 v149, v28, v29
	s_cmp_eq_u64 s[18:19], 0
	s_cbranch_scc1 .Lwt_sc_10
	global_store_dwordx4 v[154:155], v[146:149], off offset:256
.Lj_sc_10:
	s_nop 1
	v_add_u32_e32 v146, 0x90, v145
	v_mad_i64_i32 v[146:147], s[0:1], v146, s52, v[150:151]
	v_lshl_add_u64 v[154:155], v[146:147], 0, v[152:153]
	v_cvt_pk_bf16_f32 v146, v54, v55
	v_cvt_pk_bf16_f32 v147, v56, v57
	v_cvt_pk_bf16_f32 v148, v50, v51
	v_cvt_pk_bf16_f32 v149, v52, v53
	s_cmp_eq_u64 s[18:19], 0
	s_cbranch_scc1 .Lwt_sc_11
	global_store_dwordx4 v[154:155], v[146:149], off
; __device__ __forceinline__ unsigned pk_bf16(float lo, float hi) { const f32x2_t v = {lo, hi}; return __builtin_bit_cast(unsigned, __builtin_convertvector(v, bf16x2_t)); }
; template <int MODE  , class Epi, class Sched>
; __device__ __forceinline__ void gemm_phase(LAS unsigned char* lds, const GemmDesc g, const Sched& S, const Epi& E) {
;     ...
;         if (zero) {
; #pragma unroll
;             for (int a = 0; a < 2; ++a)
; #pragma unroll
;                 for (int b = 0; b < 2; ++b)
; #pragma unroll
;                     for (int m = 0; m < 4; ++m)
; #pragma unroll
;                         for (int n = 0; n < 2; ++n) acc[a][b][m][n] = (f32x4){0.f, 0.f, 0.f, 0.f};
;         }
;     __device__ __forceinline__ bool operator()(f32x4 (&acc)[2][2][4][2], const Unit& u, int wr, int wc, int fr, int fq) const {
;     ...
;             for (int m = 0; m < 4; ++m) { bf16_t* rowp = DL + (size_t)(r0 + ai * HALF + m * 16) * LDP + c0;
; #pragma unroll
;                 for (int bj = 0; bj < 2; ++bj) { const f32x4 v0 = acc[ai][bj][m][0], v1 = acc[ai][bj][m][1];
;                     u32x4 w; w.x = pk_bf16(v0[0], v0[1]); w.y = pk_bf16(v0[2], v0[3]); w.z = pk_bf16(v1[0], v1[1]); w.w = pk_bf16(v1[2], v1[3]);
;                     *(u32x4*)(rowp + bj * HALF) = w; } }
.Lj_sc_11:
	s_nop 1
	v_cvt_pk_bf16_f32 v146, v22, v23
	v_cvt_pk_bf16_f32 v147, v24, v25
	v_cvt_pk_bf16_f32 v148, v18, v19
	v_cvt_pk_bf16_f32 v149, v20, v21
	s_cmp_eq_u64 s[18:19], 0
	s_cbranch_scc1 .Lwt_sc_12
	global_store_dwordx4 v[154:155], v[146:149], off offset:256
.Lj_sc_12:
	s_nop 1
	v_add_u32_e32 v146, 0xa0, v145
	v_mad_i64_i32 v[146:147], s[0:1], v146, s52, v[150:151]
	v_lshl_add_u64 v[154:155], v[146:147], 0, v[152:153]
	v_cvt_pk_bf16_f32 v146, v46, v47
	v_cvt_pk_bf16_f32 v147, v48, v49
	v_cvt_pk_bf16_f32 v148, v42, v43
	v_cvt_pk_bf16_f32 v149, v44, v45
	s_cmp_eq_u64 s[18:19], 0
	s_cbranch_scc1 .Lwt_sc_13
	global_store_dwordx4 v[154:155], v[146:149], off
.Lj_sc_13:
	v_add_u32_e32 v145, 0xb0, v145
	s_nop 0
	v_cvt_pk_bf16_f32 v146, v14, v15
	v_cvt_pk_bf16_f32 v147, v16, v17
	v_cvt_pk_bf16_f32 v148, v10, v11
	v_cvt_pk_bf16_f32 v149, v12, v13
	s_cmp_eq_u64 s[18:19], 0
	s_cbranch_scc1 .Lwt_sc_14
	global_store_dwordx4 v[154:155], v[146:149], off offset:256
.Lj_sc_14:
	s_nop 1
	v_mad_i64_i32 v[146:147], s[0:1], v145, s52, v[150:151]
	v_lshl_add_u64 v[150:151], v[146:147], 0, v[152:153]
	v_cvt_pk_bf16_f32 v146, v38, v39
	v_cvt_pk_bf16_f32 v147, v40, v41
	v_cvt_pk_bf16_f32 v148, v34, v35
	v_cvt_pk_bf16_f32 v149, v36, v37
	s_cmp_eq_u64 s[18:19], 0
	s_cbranch_scc1 .Lwt_sc_15
	global_store_dwordx4 v[150:151], v[146:149], off
.Lj_sc_15:
	s_nop 1
	v_cvt_pk_bf16_f32 v146, v6, v7
	v_cvt_pk_bf16_f32 v147, v8, v9
	v_cvt_pk_bf16_f32 v148, v2, v3
	v_cvt_pk_bf16_f32 v149, v4, v5
	s_cmp_eq_u64 s[18:19], 0
	s_cbranch_scc1 .Lwt_sc_16
	global_store_dwordx4 v[150:151], v[146:149], off offset:256
.Lj_sc_16:
.LBB0_990:
	s_mov_b64 s[20:21], -1
	s_and_b64 vcc, exec, s[18:19]
	s_cbranch_vccz .LBB0_975
	s_andn2_b64 vcc, exec, s[34:35]
	s_cbranch_vccnz .LBB0_974
	v_mov_b32_e32 v2, 0
	v_mov_b32_e32 v3, v2
	v_mov_b64_e32 v[4:5], v[2:3]
	v_mov_b64_e32 v[6:7], v[2:3]
	v_mov_b64_e32 v[8:9], v[2:3]
	v_mov_b64_e32 v[10:11], v[2:3]
	v_mov_b64_e32 v[12:13], v[2:3]
	v_mov_b64_e32 v[14:15], v[2:3]
	v_mov_b64_e32 v[16:17], v[2:3]
	v_mov_b64_e32 v[18:19], v[2:3]
	v_mov_b64_e32 v[20:21], v[2:3]
	v_mov_b64_e32 v[22:23], v[2:3]
	v_mov_b64_e32 v[24:25], v[2:3]
	v_mov_b64_e32 v[26:27], v[2:3]
	v_mov_b64_e32 v[28:29], v[2:3]
	v_mov_b64_e32 v[30:31], v[2:3]
	v_mov_b64_e32 v[32:33], v[2:3]
	v_mov_b64_e32 v[34:35], v[2:3]
	v_mov_b64_e32 v[36:37], v[2:3]
	v_mov_b64_e32 v[38:39], v[2:3]
	v_mov_b64_e32 v[40:41], v[2:3]
	v_mov_b64_e32 v[42:43], v[2:3]
	v_mov_b64_e32 v[44:45], v[2:3]
	v_mov_b64_e32 v[46:47], v[2:3]
	v_mov_b64_e32 v[48:49], v[2:3]
	v_mov_b64_e32 v[50:51], v[2:3]
	v_mov_b64_e32 v[52:53], v[2:3]
	v_mov_b64_e32 v[54:55], v[2:3]
	v_mov_b64_e32 v[56:57], v[2:3]
	v_mov_b64_e32 v[58:59], v[2:3]
	v_mov_b64_e32 v[60:61], v[2:3]
	v_mov_b64_e32 v[62:63], v[2:3]
	v_mov_b64_e32 v[64:65], v[2:3]
	v_mov_b64_e32 v[66:67], v[2:3]
	v_mov_b64_e32 v[68:69], v[2:3]
	v_mov_b64_e32 v[70:71], v[2:3]
	v_mov_b64_e32 v[72:73], v[2:3]
	v_mov_b64_e32 v[74:75], v[2:3]
	v_mov_b64_e32 v[76:77], v[2:3]
	v_mov_b64_e32 v[78:79], v[2:3]
	v_mov_b64_e32 v[80:81], v[2:3]
	v_mov_b64_e32 v[82:83], v[2:3]
	v_mov_b64_e32 v[84:85], v[2:3]
	v_mov_b64_e32 v[86:87], v[2:3]
	v_mov_b64_e32 v[88:89], v[2:3]
	v_mov_b64_e32 v[90:91], v[2:3]
	v_mov_b64_e32 v[92:93], v[2:3]
	v_mov_b64_e32 v[94:95], v[2:3]
	v_mov_b64_e32 v[96:97], v[2:3]
	v_mov_b64_e32 v[98:99], v[2:3]
	v_mov_b64_e32 v[100:101], v[2:3]
	v_mov_b64_e32 v[102:103], v[2:3]
	v_mov_b64_e32 v[104:105], v[2:3]
	v_mov_b64_e32 v[106:107], v[2:3]
	v_mov_b64_e32 v[108:109], v[2:3]
	v_mov_b64_e32 v[110:111], v[2:3]
	v_mov_b64_e32 v[112:113], v[2:3]
	v_mov_b64_e32 v[114:115], v[2:3]
	v_mov_b64_e32 v[116:117], v[2:3]
	v_mov_b64_e32 v[118:119], v[2:3]
	v_mov_b64_e32 v[120:121], v[2:3]
	v_mov_b64_e32 v[122:123], v[2:3]
	v_mov_b64_e32 v[124:125], v[2:3]
	v_mov_b64_e32 v[126:127], v[2:3]
	v_mov_b64_e32 v[128:129], v[2:3]
	s_branch .LBB0_974
